# phase 6 conv+silu main loop hand-written: 4-row prefetch sets with counted vmcnt, 4-buffer f32 history ring, scalar per-row sequence-start test (same FMA order and silu form)
# speedup vs baseline: 1.0273x; 1.0086x over previous
; __device__ void phase_conv(const Params& p, unsigned char* smem, const int rep) {
;     ...
;   const u16* proj = (const u16*)(p.ws + OFF_PROJ);
;   u16* xbcc = (u16*)(p.ws + OFF_XBCC);
;   const int gtid = blockIdx.x * NTHR + tid;
;   const int ch0 = (gtid & 511) * 8, rb = gtid >> 9;
;   float wgt[4][8], bs[8];
; #pragma unroll
;   for (int wv = 0; wv < 4; ++wv) {
;     const float4 w0 = *(const float4*)(p.ssm_conv_w + (size_t)wv * 4096 + ch0);
;     const float4 w1 = *(const float4*)(p.ssm_conv_w + (size_t)wv * 4096 + ch0 + 4);
;     wgt[wv][0] = w0.x; wgt[wv][1] = w0.y; wgt[wv][2] = w0.z; wgt[wv][3] = w0.w;
;     wgt[wv][4] = w1.x; wgt[wv][5] = w1.y; wgt[wv][6] = w1.z; wgt[wv][7] = w1.w;
;   }
;   {
;     const float4 b0 = *(const float4*)(p.ssm_conv_b + ch0), b1 = *(const float4*)(p.ssm_conv_b + ch0 + 4);
;     bs[0] = b0.x; bs[1] = b0.y; bs[2] = b0.z; bs[3] = b0.w; bs[4] = b1.x; bs[5] = b1.y; bs[6] = b1.z; bs[7] = b1.w;
;   }
;   const int rows_per = T_TOK / (int)(gridDim.x * NTHR / 512);
;   for (int rr = 0; rr < rep; ++rr) {
;     float hm3[8], hm2[8], hm1[8];
;     const int rbeg = rb * rows_per;
;     u32x4 cur[4], nxt[4];
; #pragma unroll
;     for (int q = 0; q < 4; ++q) cur[q] = *(const u32x4*)(proj + (size_t)(rbeg + q) * PROJ_LD + 2048 + ch0);
.LBB0_1448:
	s_waitcnt vmcnt(0)
	v_lshlrev_b32_e32 v0, 3, v26
	v_and_b32_e32 v104, 0xff8, v0
	v_mov_b32_e32 v107, 0
	v_lshlrev_b32_e32 v106, 2, v104
	s_waitcnt lgkmcnt(0)
	v_lshl_add_u64 v[8:9], s[12:13], 0, v[106:107]
	s_mov_b64 s[28:29], 0x4000
	v_readlane_b32 s6, v255, 2
	v_lshl_add_u64 v[10:11], v[8:9], 0, s[28:29]
	s_mov_b64 s[30:31], 0x8000
	s_mov_b64 s[2:3], 0xc000
	v_lshl_add_u32 v0, s78, 9, v26
	v_readlane_b32 s7, v255, 3
	v_lshl_add_u64 v[12:13], v[8:9], 0, s[30:31]
	v_lshl_add_u64 v[24:25], v[8:9], 0, s[2:3]
	v_ashrrev_i32_e32 v54, 9, v0
	s_movk_i32 s2, 0x4000
	global_load_dwordx4 v[0:3], v[10:11], off offset:16
	global_load_dwordx4 v[4:7], v[12:13], off offset:16
	s_load_dword s4, s[6:7], 0x0
	s_load_dword s3, s[6:7], 0x10
	v_add_co_u32_e32 v26, vcc, s2, v8
	s_mov_b32 s2, 0x8000
	s_nop 0
	v_addc_co_u32_e32 v27, vcc, 0, v9, vcc
	s_bfe_u32 s45, s90, 0x10006
	v_add_co_u32_e32 v28, vcc, s2, v8
	s_add_u32 s26, s10, 0x4442000
	s_nop 0
	v_addc_co_u32_e32 v29, vcc, 0, v9, vcc
	s_mov_b32 s2, 0xc000
	s_addc_u32 s27, s11, 0
	v_add_co_u32_e32 v30, vcc, s2, v8
	s_waitcnt lgkmcnt(0)
	s_lshr_b32 s2, s3, 16
	s_cmp_lg_u32 s2, 0
	s_cselect_b64 s[2:3], -1, 0
	s_cmp_lg_u64 s[2:3], 0
	s_addc_u32 s2, s4, 0
	s_and_b32 s4, s2, 0x7fffff
	v_addc_co_u32_e32 v31, vcc, 0, v9, vcc
	v_cvt_f32_u32_e32 v40, s4
	global_load_dwordx4 v[8:11], v[28:29], off
	global_load_dwordx4 v[12:15], v[30:31], off
	global_load_dwordx4 v[16:19], v[26:27], off
	global_load_dwordx4 v[20:23], v[24:25], off offset:16
	s_nop 0
	global_load_dwordx4 v[24:27], v106, s[12:13] offset:16
	global_load_dwordx4 v[28:31], v106, s[14:15] offset:16
	global_load_dwordx4 v[32:35], v106, s[12:13]
	global_load_dwordx4 v[36:39], v106, s[14:15]
	s_mov_b32 s2, 0x46880000
	v_rcp_iflag_f32_e32 v41, v40
	s_movk_i32 s47, 0x3080
	v_mov_b64_e32 v[44:45], s[26:27]
	v_lshl_add_u64 v[120:121], s[0:1], 0, v[106:107]
	v_mul_f32_e32 v41, 0x46880000, v41
	v_trunc_f32_e32 v41, v41
	v_cvt_u32_f32_e32 v42, v41
	v_fma_f32 v41, -v41, v40, s2
	v_cmp_ge_f32_e64 s[2:3], |v41|, v40
	s_cmp_lg_u64 s[2:3], 0
	v_readfirstlane_b32 s5, v42
	s_addc_u32 s2, s5, 0
	v_lshlrev_b32_e32 v40, 1, v104
	v_mov_b32_e32 v41, v107
	s_and_b32 s46, s2, 0x7fffff
	v_lshl_add_u64 v[42:43], s[10:11], 0, v[40:41]
	s_mov_b64 s[2:3], 0x1e2a2000
	v_lshl_add_u64 v[110:111], v[42:43], 0, s[2:3]
	v_mad_i32_i24 v42, s46, v54, 3
	v_mad_i64_i32 v[46:47], s[2:3], v42, s47, v[44:45]
	v_lshl_add_u64 v[46:47], v[46:47], 0, v[40:41]
	s_mov_b64 s[10:11], 0x1000
	v_lshl_add_u64 v[112:113], v[46:47], 0, s[10:11]
	v_mad_i32_i24 v46, s46, v54, 2
	v_mad_i64_i32 v[48:49], s[2:3], v46, s47, v[44:45]
	v_lshl_add_u64 v[48:49], v[48:49], 0, v[40:41]
	v_lshl_add_u64 v[114:115], v[48:49], 0, s[10:11]
	v_mad_i32_i24 v48, s46, v54, 1
	v_mad_i64_i32 v[50:51], s[2:3], v48, s47, v[44:45]
	v_mul_i32_i24_e32 v108, s46, v54
	v_lshl_add_u64 v[50:51], v[50:51], 0, v[40:41]
	v_lshl_add_u64 v[116:117], v[50:51], 0, s[10:11]
	v_mad_i64_i32 v[50:51], s[2:3], v108, s47, v[44:45]
	v_mad_i32_i24 v52, s46, v54, 4
	v_lshl_add_u64 v[50:51], v[50:51], 0, v[40:41]
	v_lshl_add_u64 v[118:119], v[50:51], 0, s[10:11]
	v_mad_i64_i32 v[50:51], s[0:1], v52, s47, v[44:45]
	v_lshl_add_u64 v[50:51], v[50:51], 0, v[40:41]
	v_lshl_add_u64 v[122:123], v[50:51], 0, s[10:11]
	v_mad_i32_i24 v50, s46, v54, 5
	v_mad_i64_i32 v[50:51], s[0:1], v50, s47, v[44:45]
	v_lshl_add_u64 v[50:51], v[50:51], 0, v[40:41]
	v_lshl_add_u64 v[124:125], v[50:51], 0, s[10:11]
	v_mad_i32_i24 v50, s46, v54, 6
	v_mad_i64_i32 v[50:51], s[0:1], v50, s47, v[44:45]
	v_lshl_add_u64 v[50:51], v[50:51], 0, v[40:41]
	v_lshl_add_u64 v[126:127], v[50:51], 0, s[10:11]
	v_mad_i32_i24 v50, s46, v54, 7
	v_mad_i64_i32 v[50:51], s[0:1], v50, s47, v[44:45]
	s_movk_i32 s48, 0x3fff
	v_lshl_add_u64 v[50:51], v[50:51], 0, v[40:41]
	v_mov_b32_e32 v170, 0x7ff
	v_cmp_lt_i32_e64 s[2:3], s48, v108
	v_lshl_add_u64 v[128:129], v[50:51], 0, s[10:11]
	v_ashrrev_i32_e32 v109, 31, v108
	v_cndmask_b32_e64 v50, v170, 7, s[2:3]
	v_and_b32_e32 v55, v50, v108
	v_mov_b32_e32 v50, 0xffffc000
	v_mad_i32_i24 v50, s46, v54, v50
	v_lshrrev_b32_e32 v50, 3, v50
	v_lshl_add_u32 v106, v50, 1, v50
	v_mad_i32_i24 v50, s46, v54, -1
	v_mad_i64_i32 v[50:51], s[0:1], v50, s47, v[44:45]
	v_lshl_add_u64 v[50:51], v[50:51], 0, v[40:41]
	v_lshl_add_u64 v[130:131], v[50:51], 0, s[10:11]
	v_lshlrev_b64 v[50:51], 14, v[106:107]
	v_lshl_add_u64 v[50:51], v[120:121], 0, v[50:51]
	v_lshl_add_u64 v[132:133], v[50:51], 0, s[30:31]
	v_add_u32_e32 v50, v106, v55
	v_add_u32_e32 v106, 1, v50
	v_lshlrev_b64 v[52:53], 14, v[106:107]
	v_mad_i32_i24 v51, s46, v54, -2
	v_lshl_add_u64 v[134:135], v[120:121], 0, v[52:53]
	v_mad_i64_i32 v[52:53], s[0:1], v51, s47, v[44:45]
	v_mov_b32_e32 v51, v107
	v_lshlrev_b64 v[50:51], 14, v[50:51]
	v_lshl_add_u64 v[138:139], v[120:121], 0, v[50:51]
	v_mad_i32_i24 v50, s46, v54, -3
	v_mad_i64_i32 v[44:45], s[0:1], v50, s47, v[44:45]
	v_lshl_add_u64 v[52:53], v[52:53], 0, v[40:41]
	v_lshl_add_u64 v[40:41], v[44:45], 0, v[40:41]
	s_movk_i32 s0, 0x3ffe
	v_lshl_add_u64 v[136:137], v[52:53], 0, s[10:11]
	v_lshl_add_u64 v[140:141], v[40:41], 0, s[10:11]
	v_lshlrev_b64 v[40:41], 13, v[108:109]
	v_cmp_lt_i32_e64 s[10:11], s0, v108
	v_lshl_add_u64 v[142:143], v[110:111], 0, v[40:41]
	v_ashrrev_i32_e32 v49, 31, v48
	v_cndmask_b32_e64 v40, v170, 7, s[10:11]
	v_and_b32_e32 v40, v40, v48
	v_cmp_ne_u32_e64 s[12:13], 0, v40
	v_mov_b32_e32 v40, 0xffffc001
	v_mad_i32_i24 v40, s46, v54, v40
	v_lshrrev_b32_e32 v40, 3, v40
	v_lshl_add_u32 v106, v40, 1, v40
	v_lshlrev_b64 v[40:41], 14, v[106:107]
	s_movk_i32 s0, 0x3ffd
	v_lshl_add_u64 v[144:145], v[120:121], 0, v[40:41]
	v_lshlrev_b64 v[40:41], 13, v[48:49]
; __device__ void phase_conv(const Params& p, unsigned char* smem, const int rep) {
;     ...
;     for (int q = 0; q < 4; ++q) cur[q] = *(const u32x4*)(proj + (size_t)(rbeg + q) * PROJ_LD + 2048 + ch0);
;     for (int r4 = 0; r4 < rows_per; r4 += 4) {
; #pragma unroll
;       for (int q = 0; q < 4; ++q) {
;         nxt[q] = cur[q];
;         if (r4 + 4 + q < rows_per) nxt[q] = *(const u32x4*)(proj + (size_t)(rbeg + r4 + 4 + q) * PROJ_LD + 2048 + ch0);
;       }
; #pragma unroll
;       for (int q4 = 0; q4 < 4; ++q4) {
;         const int r = r4 + q4;
;         const int row = rbeg + r;
;         const bool samp = row >= NPROMPT;
;         const int t = samp ? ((row - NPROMPT) & 7) : (row & 2047);
;         const int b = samp ? ((row - NPROMPT) >> 3) : (row >> 11);
;         if (r == 0 || t == 0) {
; #pragma unroll
;           for (int k = 1; k <= 3; ++k) {
;             float hv[8];
;             if (t - k >= 0) {
;               unpack8(*(const u32x4*)(proj + (size_t)(row - k) * PROJ_LD + 2048 + ch0), hv);
;             } else if (samp) {
;               const float* sp = p.state_conv + ((size_t)b * 3 + (t - k + 3)) * 4096 + ch0;
;               const float4 s0 = *(const float4*)sp, s1 = *(const float4*)(sp + 4);
;               hv[0] = s0.x; hv[1] = s0.y; hv[2] = s0.z; hv[3] = s0.w; hv[4] = s1.x; hv[5] = s1.y; hv[6] = s1.z; hv[7] = s1.w;
;             } else {
; #pragma unroll
;               for (int q = 0; q < 8; ++q) hv[q] = 0.f;
;             }
; #pragma unroll
;             for (int q = 0; q < 8; ++q) {
;               if (k == 1) hm1[q] = hv[q];
;               if (k == 2) hm2[q] = hv[q];
;               if (k == 3) hm3[q] = hv[q];
;             }
;           }
;         }
	v_cmp_lt_i32_e64 s[14:15], s0, v108
	v_lshl_add_u64 v[150:151], v[110:111], 0, v[40:41]
	v_ashrrev_i32_e32 v47, 31, v46
	v_cndmask_b32_e64 v40, v170, 7, s[14:15]
	v_and_b32_e32 v40, v40, v46
	v_cmp_eq_u32_e64 s[16:17], 0, v40
	v_mov_b32_e32 v40, 0xffffc002
	v_mad_i32_i24 v40, s46, v54, v40
	v_lshrrev_b32_e32 v40, 3, v40
	v_lshl_add_u32 v106, v40, 1, v40
	v_lshlrev_b64 v[40:41], 14, v[106:107]
	s_movk_i32 s0, 0x3ffc
	v_lshl_add_u64 v[152:153], v[120:121], 0, v[40:41]
	v_lshlrev_b64 v[40:41], 13, v[46:47]
	v_cmp_lt_i32_e64 s[18:19], s0, v108
	v_lshl_add_u64 v[158:159], v[110:111], 0, v[40:41]
	s_cmpk_lt_u32 s4, 0x4401
	v_cndmask_b32_e64 v40, v170, 7, s[18:19]
	v_and_b32_e32 v40, v40, v42
	v_cmp_eq_u32_e64 s[20:21], 0, v40
	v_mov_b32_e32 v40, 0xffffc003
	v_mad_i32_i24 v40, s46, v54, v40
	v_lshrrev_b32_e32 v40, 3, v40
	s_cselect_b64 s[22:23], -1, 0
	s_cmpk_lt_u32 s4, 0xd9a
	v_lshl_add_u32 v106, v40, 1, v40
	v_ashrrev_i32_e32 v43, 31, v42
	s_cselect_b64 s[34:35], -1, 0
	s_cmpk_lt_u32 s4, 0xb56
	v_lshlrev_b64 v[40:41], 14, v[106:107]
	s_cselect_b64 s[36:37], -1, 0
	s_cmpk_lt_u32 s4, 0x9b7
	v_lshl_add_u64 v[160:161], v[120:121], 0, v[40:41]
	v_lshlrev_b64 v[40:41], 13, v[42:43]
	s_cselect_b64 s[38:39], -1, 0
	s_cmpk_lt_u32 s4, 0x881
	v_lshl_add_u64 v[166:167], v[110:111], 0, v[40:41]
	v_cndmask_b32_e64 v40, 0, 1, s[22:23]
	v_cmp_ne_u32_e64 s[4:5], 0, v55
	v_cmp_gt_u32_e64 s[6:7], 2, v55
	v_cmp_gt_u32_e64 s[8:9], 3, v55
	v_lshl_add_u64 v[146:147], v[144:145], 0, s[30:31]
	v_lshl_add_u64 v[148:149], v[144:145], 0, s[28:29]
	v_lshl_add_u64 v[154:155], v[152:153], 0, s[30:31]
	v_lshl_add_u64 v[156:157], v[152:153], 0, s[28:29]
	v_lshl_add_u64 v[162:163], v[160:161], 0, s[30:31]
	v_lshl_add_u64 v[164:165], v[160:161], 0, s[28:29]
	v_cndmask_b32_e64 v109, 0, 1, s[34:35]
	s_cselect_b64 s[40:41], -1, 0
	v_cmp_ne_u32_e64 s[22:23], 1, v40
	s_cmp_lg_u32 s96, 0x100
	s_cbranch_scc1 .LBB0_1450
	s_bitcmp1_b32 s90, 6
	s_cbranch_scc1 .LBB0_1450
	v_readlane_b32 s0, v255, 0
	v_readlane_b32 s1, v255, 1
	s_load_dwordx2 s[54:55], s[0:1], 0x20
	s_mul_i32 s56, s78, 0x44
	s_mul_i32 s57, s56, 0x3080
	s_add_u32 s57, s57, 0x4443000
	s_add_u32 s50, s84, s57
	s_addc_u32 s51, s85, 0
	s_lshl_b32 s57, s56, 13
	s_add_u32 s57, s57, 0x1e2a2000
	s_add_u32 s52, s84, s57
	s_addc_u32 s53, s85, 0
	v_lshlrev_b32_e32 v107, 1, v104
	v_lshlrev_b32_e32 v108, 1, v104
	v_mov_b32_e32 v220, 0xbfb8aa3b
	v_mov_b32_e32 v221, 0xbfb8aa3b
	v_mov_b32_e32 v222, 1.0
	v_mov_b32_e32 v223, 1.0
	s_cmp_lt_u32 s56, 0x4000
	s_cselect_b32 s57, 0x7ff, 7
	s_and_b32 s57, s56, s57
	s_cmp_eq_u32 s57, 0
	s_cbranch_scc1 .Lcv_nohist
	s_sub_u32 s58, s50, 0x9180
	s_subb_u32 s59, s51, 0
	global_load_dwordx4 v[196:199], v107, s[58:59]
	v_add_u32_e32 v109, 0x3080, v107
	global_load_dwordx4 v[200:203], v109, s[58:59]
	v_add_u32_e32 v109, 0x3080, v109
	global_load_dwordx4 v[204:207], v109, s[58:59]
	s_waitcnt vmcnt(0)
	v_lshlrev_b32_e32 v152, 16, v196
	v_and_b32_e32 v153, 0xffff0000, v196
	v_lshlrev_b32_e32 v154, 16, v197
	v_and_b32_e32 v155, 0xffff0000, v197
	v_lshlrev_b32_e32 v156, 16, v198
	v_and_b32_e32 v157, 0xffff0000, v198
	v_lshlrev_b32_e32 v158, 16, v199
	v_and_b32_e32 v159, 0xffff0000, v199
	v_lshlrev_b32_e32 v160, 16, v200
	v_and_b32_e32 v161, 0xffff0000, v200
	v_lshlrev_b32_e32 v162, 16, v201
	v_and_b32_e32 v163, 0xffff0000, v201
	v_lshlrev_b32_e32 v164, 16, v202
	v_and_b32_e32 v165, 0xffff0000, v202
	v_lshlrev_b32_e32 v166, 16, v203
	v_and_b32_e32 v167, 0xffff0000, v203
	v_lshlrev_b32_e32 v168, 16, v204
	v_and_b32_e32 v169, 0xffff0000, v204
	v_lshlrev_b32_e32 v170, 16, v205
	v_and_b32_e32 v171, 0xffff0000, v205
	v_lshlrev_b32_e32 v172, 16, v206
	v_and_b32_e32 v173, 0xffff0000, v206
	v_lshlrev_b32_e32 v174, 16, v207
	v_and_b32_e32 v175, 0xffff0000, v207
.Lcv_nohist:
	global_load_dwordx4 v[112:115], v107, s[50:51]
	v_add_u32_e32 v107, 0x3080, v107
	global_load_dwordx4 v[116:119], v107, s[50:51]
	v_add_u32_e32 v107, 0x3080, v107
	global_load_dwordx4 v[120:123], v107, s[50:51]
	v_add_u32_e32 v107, 0x3080, v107
	global_load_dwordx4 v[124:127], v107, s[50:51]
	v_add_u32_e32 v107, 0x3080, v107
	s_waitcnt vmcnt(0) lgkmcnt(0)
	s_mov_b32 s60, 0
.Lcv_loop:
	global_load_dwordx4 v[128:131], v107, s[50:51]
	v_add_u32_e32 v107, 0x3080, v107
	global_load_dwordx4 v[132:135], v107, s[50:51]
	v_add_u32_e32 v107, 0x3080, v107
	global_load_dwordx4 v[136:139], v107, s[50:51]
	v_add_u32_e32 v107, 0x3080, v107
	global_load_dwordx4 v[140:143], v107, s[50:51]
	v_add_u32_e32 v107, 0x3080, v107
	s_waitcnt vmcnt(11)
	s_cmp_lt_u32 s56, 0x4000
	s_cselect_b32 s57, 0x7ff, 7
	s_and_b32 s57, s56, s57
	s_cmp_eq_u32 s57, 0
	s_cbranch_scc0 .Lcv_a0_x
	s_cmp_lt_u32 s56, 0x4000
	s_cbranch_scc0 .Lcv_a0_s
	v_mov_b32_e32 v152, 0
	v_mov_b32_e32 v153, 0
	v_mov_b32_e32 v154, 0
	v_mov_b32_e32 v155, 0
	v_mov_b32_e32 v156, 0
	v_mov_b32_e32 v157, 0
	v_mov_b32_e32 v158, 0
	v_mov_b32_e32 v159, 0
	v_mov_b32_e32 v160, 0
	v_mov_b32_e32 v161, 0
	v_mov_b32_e32 v162, 0
	v_mov_b32_e32 v163, 0
	v_mov_b32_e32 v164, 0
	v_mov_b32_e32 v165, 0
	v_mov_b32_e32 v166, 0
	v_mov_b32_e32 v167, 0
	v_mov_b32_e32 v168, 0
	v_mov_b32_e32 v169, 0
	v_mov_b32_e32 v170, 0
	v_mov_b32_e32 v171, 0
	v_mov_b32_e32 v172, 0
	v_mov_b32_e32 v173, 0
	v_mov_b32_e32 v174, 0
	v_mov_b32_e32 v175, 0
	s_branch .Lcv_a0_x
.Lcv_a0_s:
	s_sub_u32 s57, s56, 0x4000
	s_lshr_b32 s57, s57, 3
	s_mul_i32 s57, s57, 0xc000
	v_lshl_add_u32 v109, v104, 2, s57
	global_load_dwordx4 v[152:155], v109, s[54:55] offset:0
	global_load_dwordx4 v[156:159], v109, s[54:55] offset:16
	v_add_u32_e32 v109, 0x4000, v109
	global_load_dwordx4 v[160:163], v109, s[54:55]
	global_load_dwordx4 v[164:167], v109, s[54:55] offset:16
	v_add_u32_e32 v109, 0x4000, v109
	global_load_dwordx4 v[168:171], v109, s[54:55]
	global_load_dwordx4 v[172:175], v109, s[54:55] offset:16
	s_waitcnt vmcnt(0)
; __device__ __forceinline__ float silu(float x) { return x * __builtin_amdgcn_rcpf(1.0f + __expf(-x)); }
; __device__ void phase_conv(const Params& p, unsigned char* smem, const int rep) {
;     ...
;         if (r == 0 || t == 0) {
; #pragma unroll
;           for (int k = 1; k <= 3; ++k) {
;             float hv[8];
;             if (t - k >= 0) {
;               unpack8(*(const u32x4*)(proj + (size_t)(row - k) * PROJ_LD + 2048 + ch0), hv);
;             } else if (samp) {
;               const float* sp = p.state_conv + ((size_t)b * 3 + (t - k + 3)) * 4096 + ch0;
;               const float4 s0 = *(const float4*)sp, s1 = *(const float4*)(sp + 4);
;               hv[0] = s0.x; hv[1] = s0.y; hv[2] = s0.z; hv[3] = s0.w; hv[4] = s1.x; hv[5] = s1.y; hv[6] = s1.z; hv[7] = s1.w;
;             } else {
; #pragma unroll
;               for (int q = 0; q < 8; ++q) hv[q] = 0.f;
;             }
; #pragma unroll
;             for (int q = 0; q < 8; ++q) {
;               if (k == 1) hm1[q] = hv[q];
;               if (k == 2) hm2[q] = hv[q];
;               if (k == 3) hm3[q] = hv[q];
;             }
;           }
;         }
;         float xc[8], o[8];
;         unpack8(cur[q4], xc);
; #pragma unroll
;         for (int q = 0; q < 8; ++q) {
;           const float a = bs[q] + hm3[q] * wgt[0][q] + hm2[q] * wgt[1][q] + hm1[q] * wgt[2][q] + xc[q] * wgt[3][q];
;           o[q] = silu(a);
;           hm3[q] = hm2[q]; hm2[q] = hm1[q]; hm1[q] = xc[q];
;         }
;         u32x4 ov;
;         ov.x = pack2(o[0], o[1]); ov.y = pack2(o[2], o[3]); ov.z = pack2(o[4], o[5]); ov.w = pack2(o[6], o[7]);
;         *(u32x4*)(xbcc + (size_t)row * 4096 + ch0) = ov;
.Lcv_a0_x:
	v_lshlrev_b32_e32 v144, 16, v112
	v_and_b32_e32 v145, 0xffff0000, v112
	v_lshlrev_b32_e32 v146, 16, v113
	v_and_b32_e32 v147, 0xffff0000, v113
	v_lshlrev_b32_e32 v148, 16, v114
	v_and_b32_e32 v149, 0xffff0000, v114
	v_lshlrev_b32_e32 v150, 16, v115
	v_and_b32_e32 v151, 0xffff0000, v115
	v_pk_fma_f32 v[176:177], v[32:33], v[152:153], v[36:37]
	v_pk_fma_f32 v[178:179], v[34:35], v[154:155], v[38:39]
	v_pk_fma_f32 v[180:181], v[24:25], v[156:157], v[28:29]
	v_pk_fma_f32 v[182:183], v[26:27], v[158:159], v[30:31]
	v_pk_fma_f32 v[176:177], v[16:17], v[160:161], v[176:177]
	v_pk_fma_f32 v[178:179], v[18:19], v[162:163], v[178:179]
	v_pk_fma_f32 v[180:181], v[0:1], v[164:165], v[180:181]
	v_pk_fma_f32 v[182:183], v[2:3], v[166:167], v[182:183]
	v_pk_fma_f32 v[176:177], v[8:9], v[168:169], v[176:177]
	v_pk_fma_f32 v[178:179], v[10:11], v[170:171], v[178:179]
	v_pk_fma_f32 v[180:181], v[4:5], v[172:173], v[180:181]
	v_pk_fma_f32 v[182:183], v[6:7], v[174:175], v[182:183]
	v_pk_fma_f32 v[176:177], v[12:13], v[144:145], v[176:177]
	v_pk_fma_f32 v[178:179], v[14:15], v[146:147], v[178:179]
	v_pk_fma_f32 v[180:181], v[20:21], v[148:149], v[180:181]
	v_pk_fma_f32 v[182:183], v[22:23], v[150:151], v[182:183]
	v_pk_mul_f32 v[184:185], v[176:177], v[220:221]
	v_pk_mul_f32 v[186:187], v[178:179], v[220:221]
	v_pk_mul_f32 v[188:189], v[180:181], v[220:221]
	v_pk_mul_f32 v[190:191], v[182:183], v[220:221]
	v_exp_f32_e32 v184, v184
	v_exp_f32_e32 v185, v185
	v_exp_f32_e32 v186, v186
	v_exp_f32_e32 v187, v187
	v_exp_f32_e32 v188, v188
	v_exp_f32_e32 v189, v189
	v_exp_f32_e32 v190, v190
	v_exp_f32_e32 v191, v191
	v_pk_add_f32 v[184:185], v[184:185], v[222:223]
	v_pk_add_f32 v[186:187], v[186:187], v[222:223]
	v_pk_add_f32 v[188:189], v[188:189], v[222:223]
	v_pk_add_f32 v[190:191], v[190:191], v[222:223]
	v_rcp_f32_e32 v184, v184
	v_rcp_f32_e32 v185, v185
	v_rcp_f32_e32 v186, v186
	v_rcp_f32_e32 v187, v187
	v_rcp_f32_e32 v188, v188
	v_rcp_f32_e32 v189, v189
	v_rcp_f32_e32 v190, v190
	v_rcp_f32_e32 v191, v191
	v_pk_mul_f32 v[184:185], v[176:177], v[184:185]
	v_pk_mul_f32 v[186:187], v[178:179], v[186:187]
	v_pk_mul_f32 v[188:189], v[180:181], v[188:189]
	v_pk_mul_f32 v[190:191], v[182:183], v[190:191]
	v_cvt_pk_bf16_f32 v192, v184, v185
	v_cvt_pk_bf16_f32 v193, v186, v187
	v_cvt_pk_bf16_f32 v194, v188, v189
	v_cvt_pk_bf16_f32 v195, v190, v191
	global_store_dwordx4 v108, v[192:195], s[52:53]
	v_add_u32_e32 v108, 0x2000, v108
	s_add_i32 s56, s56, 1
	s_waitcnt vmcnt(11)
	s_cmp_lt_u32 s56, 0x4000
	s_cselect_b32 s57, 0x7ff, 7
	s_and_b32 s57, s56, s57
	s_cmp_eq_u32 s57, 0
	s_cbranch_scc0 .Lcv_a1_x
	s_cmp_lt_u32 s56, 0x4000
	s_cbranch_scc0 .Lcv_a1_s
	v_mov_b32_e32 v160, 0
	v_mov_b32_e32 v161, 0
	v_mov_b32_e32 v162, 0
	v_mov_b32_e32 v163, 0
	v_mov_b32_e32 v164, 0
	v_mov_b32_e32 v165, 0
	v_mov_b32_e32 v166, 0
	v_mov_b32_e32 v167, 0
	v_mov_b32_e32 v168, 0
	v_mov_b32_e32 v169, 0
	v_mov_b32_e32 v170, 0
	v_mov_b32_e32 v171, 0
	v_mov_b32_e32 v172, 0
	v_mov_b32_e32 v173, 0
	v_mov_b32_e32 v174, 0
	v_mov_b32_e32 v175, 0
	v_mov_b32_e32 v144, 0
	v_mov_b32_e32 v145, 0
	v_mov_b32_e32 v146, 0
	v_mov_b32_e32 v147, 0
	v_mov_b32_e32 v148, 0
	v_mov_b32_e32 v149, 0
	v_mov_b32_e32 v150, 0
	v_mov_b32_e32 v151, 0
	s_branch .Lcv_a1_x
.Lcv_a1_s:
	s_sub_u32 s57, s56, 0x4000
	s_lshr_b32 s57, s57, 3
	s_mul_i32 s57, s57, 0xc000
	v_lshl_add_u32 v109, v104, 2, s57
	global_load_dwordx4 v[160:163], v109, s[54:55] offset:0
	global_load_dwordx4 v[164:167], v109, s[54:55] offset:16
	v_add_u32_e32 v109, 0x4000, v109
	global_load_dwordx4 v[168:171], v109, s[54:55]
	global_load_dwordx4 v[172:175], v109, s[54:55] offset:16
	v_add_u32_e32 v109, 0x4000, v109
	global_load_dwordx4 v[144:147], v109, s[54:55]
	global_load_dwordx4 v[148:151], v109, s[54:55] offset:16
	s_waitcnt vmcnt(0)
.Lcv_a1_x:
	v_lshlrev_b32_e32 v152, 16, v116
	v_and_b32_e32 v153, 0xffff0000, v116
	v_lshlrev_b32_e32 v154, 16, v117
	v_and_b32_e32 v155, 0xffff0000, v117
	v_lshlrev_b32_e32 v156, 16, v118
	v_and_b32_e32 v157, 0xffff0000, v118
	v_lshlrev_b32_e32 v158, 16, v119
	v_and_b32_e32 v159, 0xffff0000, v119
	v_pk_fma_f32 v[176:177], v[32:33], v[160:161], v[36:37]
	v_pk_fma_f32 v[178:179], v[34:35], v[162:163], v[38:39]
	v_pk_fma_f32 v[180:181], v[24:25], v[164:165], v[28:29]
	v_pk_fma_f32 v[182:183], v[26:27], v[166:167], v[30:31]
	v_pk_fma_f32 v[176:177], v[16:17], v[168:169], v[176:177]
	v_pk_fma_f32 v[178:179], v[18:19], v[170:171], v[178:179]
	v_pk_fma_f32 v[180:181], v[0:1], v[172:173], v[180:181]
	v_pk_fma_f32 v[182:183], v[2:3], v[174:175], v[182:183]
	v_pk_fma_f32 v[176:177], v[8:9], v[144:145], v[176:177]
	v_pk_fma_f32 v[178:179], v[10:11], v[146:147], v[178:179]
	v_pk_fma_f32 v[180:181], v[4:5], v[148:149], v[180:181]
	v_pk_fma_f32 v[182:183], v[6:7], v[150:151], v[182:183]
	v_pk_fma_f32 v[176:177], v[12:13], v[152:153], v[176:177]
	v_pk_fma_f32 v[178:179], v[14:15], v[154:155], v[178:179]
	v_pk_fma_f32 v[180:181], v[20:21], v[156:157], v[180:181]
	v_pk_fma_f32 v[182:183], v[22:23], v[158:159], v[182:183]
	v_pk_mul_f32 v[184:185], v[176:177], v[220:221]
	v_pk_mul_f32 v[186:187], v[178:179], v[220:221]
	v_pk_mul_f32 v[188:189], v[180:181], v[220:221]
	v_pk_mul_f32 v[190:191], v[182:183], v[220:221]
	v_exp_f32_e32 v184, v184
	v_exp_f32_e32 v185, v185
	v_exp_f32_e32 v186, v186
	v_exp_f32_e32 v187, v187
	v_exp_f32_e32 v188, v188
	v_exp_f32_e32 v189, v189
	v_exp_f32_e32 v190, v190
	v_exp_f32_e32 v191, v191
	v_pk_add_f32 v[184:185], v[184:185], v[222:223]
	v_pk_add_f32 v[186:187], v[186:187], v[222:223]
	v_pk_add_f32 v[188:189], v[188:189], v[222:223]
	v_pk_add_f32 v[190:191], v[190:191], v[222:223]
	v_rcp_f32_e32 v184, v184
	v_rcp_f32_e32 v185, v185
	v_rcp_f32_e32 v186, v186
	v_rcp_f32_e32 v187, v187
	v_rcp_f32_e32 v188, v188
	v_rcp_f32_e32 v189, v189
	v_rcp_f32_e32 v190, v190
	v_rcp_f32_e32 v191, v191
	v_pk_mul_f32 v[184:185], v[176:177], v[184:185]
	v_pk_mul_f32 v[186:187], v[178:179], v[186:187]
	v_pk_mul_f32 v[188:189], v[180:181], v[188:189]
	v_pk_mul_f32 v[190:191], v[182:183], v[190:191]
	v_cvt_pk_bf16_f32 v192, v184, v185
	v_cvt_pk_bf16_f32 v193, v186, v187
	v_cvt_pk_bf16_f32 v194, v188, v189
	v_cvt_pk_bf16_f32 v195, v190, v191
	global_store_dwordx4 v108, v[192:195], s[52:53]
	v_add_u32_e32 v108, 0x2000, v108
	s_add_i32 s56, s56, 1
	s_waitcnt vmcnt(11)
	s_cmp_lt_u32 s56, 0x4000
	s_cselect_b32 s57, 0x7ff, 7
	s_and_b32 s57, s56, s57
	s_cmp_eq_u32 s57, 0
	s_cbranch_scc0 .Lcv_a2_x
	s_cmp_lt_u32 s56, 0x4000
	s_cbranch_scc0 .Lcv_a2_s
	v_mov_b32_e32 v168, 0
	v_mov_b32_e32 v169, 0
	v_mov_b32_e32 v170, 0
	v_mov_b32_e32 v171, 0
	v_mov_b32_e32 v172, 0
	v_mov_b32_e32 v173, 0
	v_mov_b32_e32 v174, 0
	v_mov_b32_e32 v175, 0
	v_mov_b32_e32 v144, 0
	v_mov_b32_e32 v145, 0
	v_mov_b32_e32 v146, 0
	v_mov_b32_e32 v147, 0
	v_mov_b32_e32 v148, 0
	v_mov_b32_e32 v149, 0
	v_mov_b32_e32 v150, 0
	v_mov_b32_e32 v151, 0
	v_mov_b32_e32 v152, 0
	v_mov_b32_e32 v153, 0
	v_mov_b32_e32 v154, 0
	v_mov_b32_e32 v155, 0
	v_mov_b32_e32 v156, 0
	v_mov_b32_e32 v157, 0
	v_mov_b32_e32 v158, 0
	v_mov_b32_e32 v159, 0
	s_branch .Lcv_a2_x
; __device__ __forceinline__ float silu(float x) { return x * __builtin_amdgcn_rcpf(1.0f + __expf(-x)); }
; __device__ void phase_conv(const Params& p, unsigned char* smem, const int rep) {
;     ...
;         if (r == 0 || t == 0) {
; #pragma unroll
;           for (int k = 1; k <= 3; ++k) {
;             float hv[8];
;             if (t - k >= 0) {
;               unpack8(*(const u32x4*)(proj + (size_t)(row - k) * PROJ_LD + 2048 + ch0), hv);
;             } else if (samp) {
;               const float* sp = p.state_conv + ((size_t)b * 3 + (t - k + 3)) * 4096 + ch0;
;               const float4 s0 = *(const float4*)sp, s1 = *(const float4*)(sp + 4);
;               hv[0] = s0.x; hv[1] = s0.y; hv[2] = s0.z; hv[3] = s0.w; hv[4] = s1.x; hv[5] = s1.y; hv[6] = s1.z; hv[7] = s1.w;
;             } else {
; #pragma unroll
;               for (int q = 0; q < 8; ++q) hv[q] = 0.f;
;             }
; #pragma unroll
;             for (int q = 0; q < 8; ++q) {
;               if (k == 1) hm1[q] = hv[q];
;               if (k == 2) hm2[q] = hv[q];
;               if (k == 3) hm3[q] = hv[q];
;             }
;           }
;         }
;         float xc[8], o[8];
;         unpack8(cur[q4], xc);
; #pragma unroll
;         for (int q = 0; q < 8; ++q) {
;           const float a = bs[q] + hm3[q] * wgt[0][q] + hm2[q] * wgt[1][q] + hm1[q] * wgt[2][q] + xc[q] * wgt[3][q];
;           o[q] = silu(a);
;           hm3[q] = hm2[q]; hm2[q] = hm1[q]; hm1[q] = xc[q];
;         }
;         u32x4 ov;
;         ov.x = pack2(o[0], o[1]); ov.y = pack2(o[2], o[3]); ov.z = pack2(o[4], o[5]); ov.w = pack2(o[6], o[7]);
;         *(u32x4*)(xbcc + (size_t)row * 4096 + ch0) = ov;
.Lcv_a2_s:
	s_sub_u32 s57, s56, 0x4000
	s_lshr_b32 s57, s57, 3
	s_mul_i32 s57, s57, 0xc000
	v_lshl_add_u32 v109, v104, 2, s57
	global_load_dwordx4 v[168:171], v109, s[54:55] offset:0
	global_load_dwordx4 v[172:175], v109, s[54:55] offset:16
	v_add_u32_e32 v109, 0x4000, v109
	global_load_dwordx4 v[144:147], v109, s[54:55]
	global_load_dwordx4 v[148:151], v109, s[54:55] offset:16
	v_add_u32_e32 v109, 0x4000, v109
	global_load_dwordx4 v[152:155], v109, s[54:55]
	global_load_dwordx4 v[156:159], v109, s[54:55] offset:16
	s_waitcnt vmcnt(0)
.Lcv_a2_x:
	v_lshlrev_b32_e32 v160, 16, v120
	v_and_b32_e32 v161, 0xffff0000, v120
	v_lshlrev_b32_e32 v162, 16, v121
	v_and_b32_e32 v163, 0xffff0000, v121
	v_lshlrev_b32_e32 v164, 16, v122
	v_and_b32_e32 v165, 0xffff0000, v122
	v_lshlrev_b32_e32 v166, 16, v123
	v_and_b32_e32 v167, 0xffff0000, v123
	v_pk_fma_f32 v[176:177], v[32:33], v[168:169], v[36:37]
	v_pk_fma_f32 v[178:179], v[34:35], v[170:171], v[38:39]
	v_pk_fma_f32 v[180:181], v[24:25], v[172:173], v[28:29]
	v_pk_fma_f32 v[182:183], v[26:27], v[174:175], v[30:31]
	v_pk_fma_f32 v[176:177], v[16:17], v[144:145], v[176:177]
	v_pk_fma_f32 v[178:179], v[18:19], v[146:147], v[178:179]
	v_pk_fma_f32 v[180:181], v[0:1], v[148:149], v[180:181]
	v_pk_fma_f32 v[182:183], v[2:3], v[150:151], v[182:183]
	v_pk_fma_f32 v[176:177], v[8:9], v[152:153], v[176:177]
	v_pk_fma_f32 v[178:179], v[10:11], v[154:155], v[178:179]
	v_pk_fma_f32 v[180:181], v[4:5], v[156:157], v[180:181]
	v_pk_fma_f32 v[182:183], v[6:7], v[158:159], v[182:183]
	v_pk_fma_f32 v[176:177], v[12:13], v[160:161], v[176:177]
	v_pk_fma_f32 v[178:179], v[14:15], v[162:163], v[178:179]
	v_pk_fma_f32 v[180:181], v[20:21], v[164:165], v[180:181]
	v_pk_fma_f32 v[182:183], v[22:23], v[166:167], v[182:183]
	v_pk_mul_f32 v[184:185], v[176:177], v[220:221]
	v_pk_mul_f32 v[186:187], v[178:179], v[220:221]
	v_pk_mul_f32 v[188:189], v[180:181], v[220:221]
	v_pk_mul_f32 v[190:191], v[182:183], v[220:221]
	v_exp_f32_e32 v184, v184
	v_exp_f32_e32 v185, v185
	v_exp_f32_e32 v186, v186
	v_exp_f32_e32 v187, v187
	v_exp_f32_e32 v188, v188
	v_exp_f32_e32 v189, v189
	v_exp_f32_e32 v190, v190
	v_exp_f32_e32 v191, v191
	v_pk_add_f32 v[184:185], v[184:185], v[222:223]
	v_pk_add_f32 v[186:187], v[186:187], v[222:223]
	v_pk_add_f32 v[188:189], v[188:189], v[222:223]
	v_pk_add_f32 v[190:191], v[190:191], v[222:223]
	v_rcp_f32_e32 v184, v184
	v_rcp_f32_e32 v185, v185
	v_rcp_f32_e32 v186, v186
	v_rcp_f32_e32 v187, v187
	v_rcp_f32_e32 v188, v188
	v_rcp_f32_e32 v189, v189
	v_rcp_f32_e32 v190, v190
	v_rcp_f32_e32 v191, v191
	v_pk_mul_f32 v[184:185], v[176:177], v[184:185]
	v_pk_mul_f32 v[186:187], v[178:179], v[186:187]
	v_pk_mul_f32 v[188:189], v[180:181], v[188:189]
	v_pk_mul_f32 v[190:191], v[182:183], v[190:191]
	v_cvt_pk_bf16_f32 v192, v184, v185
	v_cvt_pk_bf16_f32 v193, v186, v187
	v_cvt_pk_bf16_f32 v194, v188, v189
	v_cvt_pk_bf16_f32 v195, v190, v191
	global_store_dwordx4 v108, v[192:195], s[52:53]
	v_add_u32_e32 v108, 0x2000, v108
	s_add_i32 s56, s56, 1
	s_waitcnt vmcnt(11)
	s_cmp_lt_u32 s56, 0x4000
	s_cselect_b32 s57, 0x7ff, 7
	s_and_b32 s57, s56, s57
	s_cmp_eq_u32 s57, 0
	s_cbranch_scc0 .Lcv_a3_x
	s_cmp_lt_u32 s56, 0x4000
	s_cbranch_scc0 .Lcv_a3_s
	v_mov_b32_e32 v144, 0
	v_mov_b32_e32 v145, 0
	v_mov_b32_e32 v146, 0
	v_mov_b32_e32 v147, 0
	v_mov_b32_e32 v148, 0
	v_mov_b32_e32 v149, 0
	v_mov_b32_e32 v150, 0
	v_mov_b32_e32 v151, 0
	v_mov_b32_e32 v152, 0
	v_mov_b32_e32 v153, 0
	v_mov_b32_e32 v154, 0
	v_mov_b32_e32 v155, 0
	v_mov_b32_e32 v156, 0
	v_mov_b32_e32 v157, 0
	v_mov_b32_e32 v158, 0
	v_mov_b32_e32 v159, 0
	v_mov_b32_e32 v160, 0
	v_mov_b32_e32 v161, 0
	v_mov_b32_e32 v162, 0
	v_mov_b32_e32 v163, 0
	v_mov_b32_e32 v164, 0
	v_mov_b32_e32 v165, 0
	v_mov_b32_e32 v166, 0
	v_mov_b32_e32 v167, 0
	s_branch .Lcv_a3_x
; __device__ __forceinline__ float silu(float x) { return x * __builtin_amdgcn_rcpf(1.0f + __expf(-x)); }
; __device__ void phase_conv(const Params& p, unsigned char* smem, const int rep) {
;     ...
;     for (int r4 = 0; r4 < rows_per; r4 += 4) {
; #pragma unroll
;       for (int q = 0; q < 4; ++q) {
;         nxt[q] = cur[q];
;         if (r4 + 4 + q < rows_per) nxt[q] = *(const u32x4*)(proj + (size_t)(rbeg + r4 + 4 + q) * PROJ_LD + 2048 + ch0);
;       }
; #pragma unroll
;       for (int q4 = 0; q4 < 4; ++q4) {
;         const int r = r4 + q4;
;         const int row = rbeg + r;
;         const bool samp = row >= NPROMPT;
;         const int t = samp ? ((row - NPROMPT) & 7) : (row & 2047);
;         const int b = samp ? ((row - NPROMPT) >> 3) : (row >> 11);
;         if (r == 0 || t == 0) {
; #pragma unroll
;           for (int k = 1; k <= 3; ++k) {
;             float hv[8];
;             if (t - k >= 0) {
;               unpack8(*(const u32x4*)(proj + (size_t)(row - k) * PROJ_LD + 2048 + ch0), hv);
;             } else if (samp) {
;               const float* sp = p.state_conv + ((size_t)b * 3 + (t - k + 3)) * 4096 + ch0;
;               const float4 s0 = *(const float4*)sp, s1 = *(const float4*)(sp + 4);
;               hv[0] = s0.x; hv[1] = s0.y; hv[2] = s0.z; hv[3] = s0.w; hv[4] = s1.x; hv[5] = s1.y; hv[6] = s1.z; hv[7] = s1.w;
;             } else {
; #pragma unroll
;               for (int q = 0; q < 8; ++q) hv[q] = 0.f;
;             }
; #pragma unroll
;             for (int q = 0; q < 8; ++q) {
;               if (k == 1) hm1[q] = hv[q];
;               if (k == 2) hm2[q] = hv[q];
;               if (k == 3) hm3[q] = hv[q];
;             }
;           }
;         }
;         float xc[8], o[8];
;         unpack8(cur[q4], xc);
; #pragma unroll
;         for (int q = 0; q < 8; ++q) {
;           const float a = bs[q] + hm3[q] * wgt[0][q] + hm2[q] * wgt[1][q] + hm1[q] * wgt[2][q] + xc[q] * wgt[3][q];
;           o[q] = silu(a);
;           hm3[q] = hm2[q]; hm2[q] = hm1[q]; hm1[q] = xc[q];
;         }
;         u32x4 ov;
;         ov.x = pack2(o[0], o[1]); ov.y = pack2(o[2], o[3]); ov.z = pack2(o[4], o[5]); ov.w = pack2(o[6], o[7]);
;         *(u32x4*)(xbcc + (size_t)row * 4096 + ch0) = ov;
.Lcv_a3_s:
	s_sub_u32 s57, s56, 0x4000
	s_lshr_b32 s57, s57, 3
	s_mul_i32 s57, s57, 0xc000
	v_lshl_add_u32 v109, v104, 2, s57
	global_load_dwordx4 v[144:147], v109, s[54:55] offset:0
	global_load_dwordx4 v[148:151], v109, s[54:55] offset:16
	v_add_u32_e32 v109, 0x4000, v109
	global_load_dwordx4 v[152:155], v109, s[54:55]
	global_load_dwordx4 v[156:159], v109, s[54:55] offset:16
	v_add_u32_e32 v109, 0x4000, v109
	global_load_dwordx4 v[160:163], v109, s[54:55]
	global_load_dwordx4 v[164:167], v109, s[54:55] offset:16
	s_waitcnt vmcnt(0)
.Lcv_a3_x:
	v_lshlrev_b32_e32 v168, 16, v124
	v_and_b32_e32 v169, 0xffff0000, v124
	v_lshlrev_b32_e32 v170, 16, v125
	v_and_b32_e32 v171, 0xffff0000, v125
	v_lshlrev_b32_e32 v172, 16, v126
	v_and_b32_e32 v173, 0xffff0000, v126
	v_lshlrev_b32_e32 v174, 16, v127
	v_and_b32_e32 v175, 0xffff0000, v127
	v_pk_fma_f32 v[176:177], v[32:33], v[144:145], v[36:37]
	v_pk_fma_f32 v[178:179], v[34:35], v[146:147], v[38:39]
	v_pk_fma_f32 v[180:181], v[24:25], v[148:149], v[28:29]
	v_pk_fma_f32 v[182:183], v[26:27], v[150:151], v[30:31]
	v_pk_fma_f32 v[176:177], v[16:17], v[152:153], v[176:177]
	v_pk_fma_f32 v[178:179], v[18:19], v[154:155], v[178:179]
	v_pk_fma_f32 v[180:181], v[0:1], v[156:157], v[180:181]
	v_pk_fma_f32 v[182:183], v[2:3], v[158:159], v[182:183]
	v_pk_fma_f32 v[176:177], v[8:9], v[160:161], v[176:177]
	v_pk_fma_f32 v[178:179], v[10:11], v[162:163], v[178:179]
	v_pk_fma_f32 v[180:181], v[4:5], v[164:165], v[180:181]
	v_pk_fma_f32 v[182:183], v[6:7], v[166:167], v[182:183]
	v_pk_fma_f32 v[176:177], v[12:13], v[168:169], v[176:177]
	v_pk_fma_f32 v[178:179], v[14:15], v[170:171], v[178:179]
	v_pk_fma_f32 v[180:181], v[20:21], v[172:173], v[180:181]
	v_pk_fma_f32 v[182:183], v[22:23], v[174:175], v[182:183]
	v_pk_mul_f32 v[184:185], v[176:177], v[220:221]
	v_pk_mul_f32 v[186:187], v[178:179], v[220:221]
	v_pk_mul_f32 v[188:189], v[180:181], v[220:221]
	v_pk_mul_f32 v[190:191], v[182:183], v[220:221]
	v_exp_f32_e32 v184, v184
	v_exp_f32_e32 v185, v185
	v_exp_f32_e32 v186, v186
	v_exp_f32_e32 v187, v187
	v_exp_f32_e32 v188, v188
	v_exp_f32_e32 v189, v189
	v_exp_f32_e32 v190, v190
	v_exp_f32_e32 v191, v191
	v_pk_add_f32 v[184:185], v[184:185], v[222:223]
	v_pk_add_f32 v[186:187], v[186:187], v[222:223]
	v_pk_add_f32 v[188:189], v[188:189], v[222:223]
	v_pk_add_f32 v[190:191], v[190:191], v[222:223]
	v_rcp_f32_e32 v184, v184
	v_rcp_f32_e32 v185, v185
	v_rcp_f32_e32 v186, v186
	v_rcp_f32_e32 v187, v187
	v_rcp_f32_e32 v188, v188
	v_rcp_f32_e32 v189, v189
	v_rcp_f32_e32 v190, v190
	v_rcp_f32_e32 v191, v191
	v_pk_mul_f32 v[184:185], v[176:177], v[184:185]
	v_pk_mul_f32 v[186:187], v[178:179], v[186:187]
	v_pk_mul_f32 v[188:189], v[180:181], v[188:189]
	v_pk_mul_f32 v[190:191], v[182:183], v[190:191]
	v_cvt_pk_bf16_f32 v192, v184, v185
	v_cvt_pk_bf16_f32 v193, v186, v187
	v_cvt_pk_bf16_f32 v194, v188, v189
	v_cvt_pk_bf16_f32 v195, v190, v191
	global_store_dwordx4 v108, v[192:195], s[52:53]
	v_add_u32_e32 v108, 0x2000, v108
	s_add_i32 s56, s56, 1
	global_load_dwordx4 v[112:115], v107, s[50:51]
	v_add_u32_e32 v107, 0x3080, v107
	global_load_dwordx4 v[116:119], v107, s[50:51]
	v_add_u32_e32 v107, 0x3080, v107
	global_load_dwordx4 v[120:123], v107, s[50:51]
	v_add_u32_e32 v107, 0x3080, v107
	global_load_dwordx4 v[124:127], v107, s[50:51]
	v_add_u32_e32 v107, 0x3080, v107
	s_waitcnt vmcnt(11)
	s_cmp_lt_u32 s56, 0x4000
	s_cselect_b32 s57, 0x7ff, 7
	s_and_b32 s57, s56, s57
	s_cmp_eq_u32 s57, 0
	s_cbranch_scc0 .Lcv_b0_x
	s_cmp_lt_u32 s56, 0x4000
	s_cbranch_scc0 .Lcv_b0_s
	v_mov_b32_e32 v152, 0
	v_mov_b32_e32 v153, 0
	v_mov_b32_e32 v154, 0
	v_mov_b32_e32 v155, 0
	v_mov_b32_e32 v156, 0
	v_mov_b32_e32 v157, 0
	v_mov_b32_e32 v158, 0
	v_mov_b32_e32 v159, 0
	v_mov_b32_e32 v160, 0
	v_mov_b32_e32 v161, 0
	v_mov_b32_e32 v162, 0
	v_mov_b32_e32 v163, 0
	v_mov_b32_e32 v164, 0
	v_mov_b32_e32 v165, 0
	v_mov_b32_e32 v166, 0
	v_mov_b32_e32 v167, 0
	v_mov_b32_e32 v168, 0
	v_mov_b32_e32 v169, 0
	v_mov_b32_e32 v170, 0
	v_mov_b32_e32 v171, 0
	v_mov_b32_e32 v172, 0
	v_mov_b32_e32 v173, 0
	v_mov_b32_e32 v174, 0
	v_mov_b32_e32 v175, 0
	s_branch .Lcv_b0_x

; __device__ __forceinline__ float silu(float x) { return x * __builtin_amdgcn_rcpf(1.0f + __expf(-x)); }
; __device__ void phase_conv(const Params& p, unsigned char* smem, const int rep) {
;     ...
;         if (r == 0 || t == 0) {
; #pragma unroll
;           for (int k = 1; k <= 3; ++k) {
;             float hv[8];
;             if (t - k >= 0) {
;               unpack8(*(const u32x4*)(proj + (size_t)(row - k) * PROJ_LD + 2048 + ch0), hv);
;             } else if (samp) {
;               const float* sp = p.state_conv + ((size_t)b * 3 + (t - k + 3)) * 4096 + ch0;
;               const float4 s0 = *(const float4*)sp, s1 = *(const float4*)(sp + 4);
;               hv[0] = s0.x; hv[1] = s0.y; hv[2] = s0.z; hv[3] = s0.w; hv[4] = s1.x; hv[5] = s1.y; hv[6] = s1.z; hv[7] = s1.w;
;             } else {
; #pragma unroll
;               for (int q = 0; q < 8; ++q) hv[q] = 0.f;
;             }
; #pragma unroll
;             for (int q = 0; q < 8; ++q) {
;               if (k == 1) hm1[q] = hv[q];
;               if (k == 2) hm2[q] = hv[q];
;               if (k == 3) hm3[q] = hv[q];
;             }
;           }
;         }
;         float xc[8], o[8];
;         unpack8(cur[q4], xc);
; #pragma unroll
;         for (int q = 0; q < 8; ++q) {
;           const float a = bs[q] + hm3[q] * wgt[0][q] + hm2[q] * wgt[1][q] + hm1[q] * wgt[2][q] + xc[q] * wgt[3][q];
;           o[q] = silu(a);
;           hm3[q] = hm2[q]; hm2[q] = hm1[q]; hm1[q] = xc[q];
;         }
;         u32x4 ov;
;         ov.x = pack2(o[0], o[1]); ov.y = pack2(o[2], o[3]); ov.z = pack2(o[4], o[5]); ov.w = pack2(o[6], o[7]);
;         *(u32x4*)(xbcc + (size_t)row * 4096 + ch0) = ov;
.Lcv_b0_x:
	v_lshlrev_b32_e32 v144, 16, v128
	v_and_b32_e32 v145, 0xffff0000, v128
	v_lshlrev_b32_e32 v146, 16, v129
	v_and_b32_e32 v147, 0xffff0000, v129
	v_lshlrev_b32_e32 v148, 16, v130
	v_and_b32_e32 v149, 0xffff0000, v130
	v_lshlrev_b32_e32 v150, 16, v131
	v_and_b32_e32 v151, 0xffff0000, v131
	v_pk_fma_f32 v[176:177], v[32:33], v[152:153], v[36:37]
	v_pk_fma_f32 v[178:179], v[34:35], v[154:155], v[38:39]
	v_pk_fma_f32 v[180:181], v[24:25], v[156:157], v[28:29]
	v_pk_fma_f32 v[182:183], v[26:27], v[158:159], v[30:31]
	v_pk_fma_f32 v[176:177], v[16:17], v[160:161], v[176:177]
	v_pk_fma_f32 v[178:179], v[18:19], v[162:163], v[178:179]
	v_pk_fma_f32 v[180:181], v[0:1], v[164:165], v[180:181]
	v_pk_fma_f32 v[182:183], v[2:3], v[166:167], v[182:183]
	v_pk_fma_f32 v[176:177], v[8:9], v[168:169], v[176:177]
	v_pk_fma_f32 v[178:179], v[10:11], v[170:171], v[178:179]
	v_pk_fma_f32 v[180:181], v[4:5], v[172:173], v[180:181]
	v_pk_fma_f32 v[182:183], v[6:7], v[174:175], v[182:183]
	v_pk_fma_f32 v[176:177], v[12:13], v[144:145], v[176:177]
	v_pk_fma_f32 v[178:179], v[14:15], v[146:147], v[178:179]
	v_pk_fma_f32 v[180:181], v[20:21], v[148:149], v[180:181]
	v_pk_fma_f32 v[182:183], v[22:23], v[150:151], v[182:183]
	v_pk_mul_f32 v[184:185], v[176:177], v[220:221]
	v_pk_mul_f32 v[186:187], v[178:179], v[220:221]
	v_pk_mul_f32 v[188:189], v[180:181], v[220:221]
	v_pk_mul_f32 v[190:191], v[182:183], v[220:221]
	v_exp_f32_e32 v184, v184
	v_exp_f32_e32 v185, v185
	v_exp_f32_e32 v186, v186
	v_exp_f32_e32 v187, v187
	v_exp_f32_e32 v188, v188
	v_exp_f32_e32 v189, v189
	v_exp_f32_e32 v190, v190
	v_exp_f32_e32 v191, v191
	v_pk_add_f32 v[184:185], v[184:185], v[222:223]
	v_pk_add_f32 v[186:187], v[186:187], v[222:223]
	v_pk_add_f32 v[188:189], v[188:189], v[222:223]
	v_pk_add_f32 v[190:191], v[190:191], v[222:223]
	v_rcp_f32_e32 v184, v184
	v_rcp_f32_e32 v185, v185
	v_rcp_f32_e32 v186, v186
	v_rcp_f32_e32 v187, v187
	v_rcp_f32_e32 v188, v188
	v_rcp_f32_e32 v189, v189
	v_rcp_f32_e32 v190, v190
	v_rcp_f32_e32 v191, v191
	v_pk_mul_f32 v[184:185], v[176:177], v[184:185]
	v_pk_mul_f32 v[186:187], v[178:179], v[186:187]
	v_pk_mul_f32 v[188:189], v[180:181], v[188:189]
	v_pk_mul_f32 v[190:191], v[182:183], v[190:191]
	v_cvt_pk_bf16_f32 v192, v184, v185
	v_cvt_pk_bf16_f32 v193, v186, v187
	v_cvt_pk_bf16_f32 v194, v188, v189
	v_cvt_pk_bf16_f32 v195, v190, v191
	global_store_dwordx4 v108, v[192:195], s[52:53]
	v_add_u32_e32 v108, 0x2000, v108
	s_add_i32 s56, s56, 1
	s_waitcnt vmcnt(11)
	s_cmp_lt_u32 s56, 0x4000
	s_cselect_b32 s57, 0x7ff, 7
	s_and_b32 s57, s56, s57
	s_cmp_eq_u32 s57, 0
	s_cbranch_scc0 .Lcv_b1_x
	s_cmp_lt_u32 s56, 0x4000
	s_cbranch_scc0 .Lcv_b1_s
	v_mov_b32_e32 v160, 0
	v_mov_b32_e32 v161, 0
	v_mov_b32_e32 v162, 0
	v_mov_b32_e32 v163, 0
	v_mov_b32_e32 v164, 0
	v_mov_b32_e32 v165, 0
	v_mov_b32_e32 v166, 0
	v_mov_b32_e32 v167, 0
	v_mov_b32_e32 v168, 0
	v_mov_b32_e32 v169, 0
	v_mov_b32_e32 v170, 0
	v_mov_b32_e32 v171, 0
	v_mov_b32_e32 v172, 0
	v_mov_b32_e32 v173, 0
	v_mov_b32_e32 v174, 0
	v_mov_b32_e32 v175, 0
	v_mov_b32_e32 v144, 0
	v_mov_b32_e32 v145, 0
	v_mov_b32_e32 v146, 0
	v_mov_b32_e32 v147, 0
	v_mov_b32_e32 v148, 0
	v_mov_b32_e32 v149, 0
	v_mov_b32_e32 v150, 0
	v_mov_b32_e32 v151, 0
	s_branch .Lcv_b1_x

; __device__ __forceinline__ float silu(float x) { return x * __builtin_amdgcn_rcpf(1.0f + __expf(-x)); }
; __device__ void phase_conv(const Params& p, unsigned char* smem, const int rep) {
;     ...
;         if (r == 0 || t == 0) {
; #pragma unroll
;           for (int k = 1; k <= 3; ++k) {
;             float hv[8];
;             if (t - k >= 0) {
;               unpack8(*(const u32x4*)(proj + (size_t)(row - k) * PROJ_LD + 2048 + ch0), hv);
;             } else if (samp) {
;               const float* sp = p.state_conv + ((size_t)b * 3 + (t - k + 3)) * 4096 + ch0;
;               const float4 s0 = *(const float4*)sp, s1 = *(const float4*)(sp + 4);
;               hv[0] = s0.x; hv[1] = s0.y; hv[2] = s0.z; hv[3] = s0.w; hv[4] = s1.x; hv[5] = s1.y; hv[6] = s1.z; hv[7] = s1.w;
;             } else {
; #pragma unroll
;               for (int q = 0; q < 8; ++q) hv[q] = 0.f;
;             }
; #pragma unroll
;             for (int q = 0; q < 8; ++q) {
;               if (k == 1) hm1[q] = hv[q];
;               if (k == 2) hm2[q] = hv[q];
;               if (k == 3) hm3[q] = hv[q];
;             }
;           }
;         }
;         float xc[8], o[8];
;         unpack8(cur[q4], xc);
; #pragma unroll
;         for (int q = 0; q < 8; ++q) {
;           const float a = bs[q] + hm3[q] * wgt[0][q] + hm2[q] * wgt[1][q] + hm1[q] * wgt[2][q] + xc[q] * wgt[3][q];
;           o[q] = silu(a);
;           hm3[q] = hm2[q]; hm2[q] = hm1[q]; hm1[q] = xc[q];
;         }
;         u32x4 ov;
;         ov.x = pack2(o[0], o[1]); ov.y = pack2(o[2], o[3]); ov.z = pack2(o[4], o[5]); ov.w = pack2(o[6], o[7]);
;         *(u32x4*)(xbcc + (size_t)row * 4096 + ch0) = ov;
.Lcv_b1_x:
	v_lshlrev_b32_e32 v152, 16, v132
	v_and_b32_e32 v153, 0xffff0000, v132
	v_lshlrev_b32_e32 v154, 16, v133
	v_and_b32_e32 v155, 0xffff0000, v133
	v_lshlrev_b32_e32 v156, 16, v134
	v_and_b32_e32 v157, 0xffff0000, v134
	v_lshlrev_b32_e32 v158, 16, v135
	v_and_b32_e32 v159, 0xffff0000, v135
	v_pk_fma_f32 v[176:177], v[32:33], v[160:161], v[36:37]
	v_pk_fma_f32 v[178:179], v[34:35], v[162:163], v[38:39]
	v_pk_fma_f32 v[180:181], v[24:25], v[164:165], v[28:29]
	v_pk_fma_f32 v[182:183], v[26:27], v[166:167], v[30:31]
	v_pk_fma_f32 v[176:177], v[16:17], v[168:169], v[176:177]
	v_pk_fma_f32 v[178:179], v[18:19], v[170:171], v[178:179]
	v_pk_fma_f32 v[180:181], v[0:1], v[172:173], v[180:181]
	v_pk_fma_f32 v[182:183], v[2:3], v[174:175], v[182:183]
	v_pk_fma_f32 v[176:177], v[8:9], v[144:145], v[176:177]
	v_pk_fma_f32 v[178:179], v[10:11], v[146:147], v[178:179]
	v_pk_fma_f32 v[180:181], v[4:5], v[148:149], v[180:181]
	v_pk_fma_f32 v[182:183], v[6:7], v[150:151], v[182:183]
	v_pk_fma_f32 v[176:177], v[12:13], v[152:153], v[176:177]
	v_pk_fma_f32 v[178:179], v[14:15], v[154:155], v[178:179]
	v_pk_fma_f32 v[180:181], v[20:21], v[156:157], v[180:181]
	v_pk_fma_f32 v[182:183], v[22:23], v[158:159], v[182:183]
	v_pk_mul_f32 v[184:185], v[176:177], v[220:221]
	v_pk_mul_f32 v[186:187], v[178:179], v[220:221]
	v_pk_mul_f32 v[188:189], v[180:181], v[220:221]
	v_pk_mul_f32 v[190:191], v[182:183], v[220:221]
	v_exp_f32_e32 v184, v184
	v_exp_f32_e32 v185, v185
	v_exp_f32_e32 v186, v186
	v_exp_f32_e32 v187, v187
	v_exp_f32_e32 v188, v188
	v_exp_f32_e32 v189, v189
	v_exp_f32_e32 v190, v190
	v_exp_f32_e32 v191, v191
	v_pk_add_f32 v[184:185], v[184:185], v[222:223]
	v_pk_add_f32 v[186:187], v[186:187], v[222:223]
	v_pk_add_f32 v[188:189], v[188:189], v[222:223]
	v_pk_add_f32 v[190:191], v[190:191], v[222:223]
	v_rcp_f32_e32 v184, v184
	v_rcp_f32_e32 v185, v185
	v_rcp_f32_e32 v186, v186
	v_rcp_f32_e32 v187, v187
	v_rcp_f32_e32 v188, v188
	v_rcp_f32_e32 v189, v189
	v_rcp_f32_e32 v190, v190
	v_rcp_f32_e32 v191, v191
	v_pk_mul_f32 v[184:185], v[176:177], v[184:185]
	v_pk_mul_f32 v[186:187], v[178:179], v[186:187]
	v_pk_mul_f32 v[188:189], v[180:181], v[188:189]
	v_pk_mul_f32 v[190:191], v[182:183], v[190:191]
	v_cvt_pk_bf16_f32 v192, v184, v185
	v_cvt_pk_bf16_f32 v193, v186, v187
	v_cvt_pk_bf16_f32 v194, v188, v189
	v_cvt_pk_bf16_f32 v195, v190, v191
	global_store_dwordx4 v108, v[192:195], s[52:53]
	v_add_u32_e32 v108, 0x2000, v108
	s_add_i32 s56, s56, 1
	s_waitcnt vmcnt(11)
	s_cmp_lt_u32 s56, 0x4000
	s_cselect_b32 s57, 0x7ff, 7
	s_and_b32 s57, s56, s57
	s_cmp_eq_u32 s57, 0
	s_cbranch_scc0 .Lcv_b2_x
	s_cmp_lt_u32 s56, 0x4000
	s_cbranch_scc0 .Lcv_b2_s
	v_mov_b32_e32 v168, 0
	v_mov_b32_e32 v169, 0
	v_mov_b32_e32 v170, 0
	v_mov_b32_e32 v171, 0
	v_mov_b32_e32 v172, 0
	v_mov_b32_e32 v173, 0
	v_mov_b32_e32 v174, 0
	v_mov_b32_e32 v175, 0
	v_mov_b32_e32 v144, 0
	v_mov_b32_e32 v145, 0
	v_mov_b32_e32 v146, 0
	v_mov_b32_e32 v147, 0
	v_mov_b32_e32 v148, 0
	v_mov_b32_e32 v149, 0
	v_mov_b32_e32 v150, 0
	v_mov_b32_e32 v151, 0
	v_mov_b32_e32 v152, 0
	v_mov_b32_e32 v153, 0
	v_mov_b32_e32 v154, 0
	v_mov_b32_e32 v155, 0
	v_mov_b32_e32 v156, 0
	v_mov_b32_e32 v157, 0
	v_mov_b32_e32 v158, 0
	v_mov_b32_e32 v159, 0
	s_branch .Lcv_b2_x

; __device__ __forceinline__ float silu(float x) { return x * __builtin_amdgcn_rcpf(1.0f + __expf(-x)); }
; __device__ void phase_conv(const Params& p, unsigned char* smem, const int rep) {
;     ...
;         const bool samp = row >= NPROMPT;
;         const int t = samp ? ((row - NPROMPT) & 7) : (row & 2047);
;         const int b = samp ? ((row - NPROMPT) >> 3) : (row >> 11);
;         if (r == 0 || t == 0) {
; #pragma unroll
;           for (int k = 1; k <= 3; ++k) {
;             float hv[8];
;             if (t - k >= 0) {
;               unpack8(*(const u32x4*)(proj + (size_t)(row - k) * PROJ_LD + 2048 + ch0), hv);
;             } else if (samp) {
;               const float* sp = p.state_conv + ((size_t)b * 3 + (t - k + 3)) * 4096 + ch0;
;               const float4 s0 = *(const float4*)sp, s1 = *(const float4*)(sp + 4);
;               hv[0] = s0.x; hv[1] = s0.y; hv[2] = s0.z; hv[3] = s0.w; hv[4] = s1.x; hv[5] = s1.y; hv[6] = s1.z; hv[7] = s1.w;
;             } else {
; #pragma unroll
;               for (int q = 0; q < 8; ++q) hv[q] = 0.f;
;     ...
;         float xc[8], o[8];
;         unpack8(cur[q4], xc);
; #pragma unroll
;         for (int q = 0; q < 8; ++q) {
;           const float a = bs[q] + hm3[q] * wgt[0][q] + hm2[q] * wgt[1][q] + hm1[q] * wgt[2][q] + xc[q] * wgt[3][q];
;           o[q] = silu(a);
;           hm3[q] = hm2[q]; hm2[q] = hm1[q]; hm1[q] = xc[q];
;         }
;         u32x4 ov;
;         ov.x = pack2(o[0], o[1]); ov.y = pack2(o[2], o[3]); ov.z = pack2(o[4], o[5]); ov.w = pack2(o[6], o[7]);
;         *(u32x4*)(xbcc + (size_t)row * 4096 + ch0) = ov;
.Lcv_b2_x:
	v_lshlrev_b32_e32 v160, 16, v136
	v_and_b32_e32 v161, 0xffff0000, v136
	v_lshlrev_b32_e32 v162, 16, v137
	v_and_b32_e32 v163, 0xffff0000, v137
	v_lshlrev_b32_e32 v164, 16, v138
	v_and_b32_e32 v165, 0xffff0000, v138
	v_lshlrev_b32_e32 v166, 16, v139
	v_and_b32_e32 v167, 0xffff0000, v139
	v_pk_fma_f32 v[176:177], v[32:33], v[168:169], v[36:37]
	v_pk_fma_f32 v[178:179], v[34:35], v[170:171], v[38:39]
	v_pk_fma_f32 v[180:181], v[24:25], v[172:173], v[28:29]
	v_pk_fma_f32 v[182:183], v[26:27], v[174:175], v[30:31]
	v_pk_fma_f32 v[176:177], v[16:17], v[144:145], v[176:177]
	v_pk_fma_f32 v[178:179], v[18:19], v[146:147], v[178:179]
	v_pk_fma_f32 v[180:181], v[0:1], v[148:149], v[180:181]
	v_pk_fma_f32 v[182:183], v[2:3], v[150:151], v[182:183]
	v_pk_fma_f32 v[176:177], v[8:9], v[152:153], v[176:177]
	v_pk_fma_f32 v[178:179], v[10:11], v[154:155], v[178:179]
	v_pk_fma_f32 v[180:181], v[4:5], v[156:157], v[180:181]
	v_pk_fma_f32 v[182:183], v[6:7], v[158:159], v[182:183]
	v_pk_fma_f32 v[176:177], v[12:13], v[160:161], v[176:177]
	v_pk_fma_f32 v[178:179], v[14:15], v[162:163], v[178:179]
	v_pk_fma_f32 v[180:181], v[20:21], v[164:165], v[180:181]
	v_pk_fma_f32 v[182:183], v[22:23], v[166:167], v[182:183]
	v_pk_mul_f32 v[184:185], v[176:177], v[220:221]
	v_pk_mul_f32 v[186:187], v[178:179], v[220:221]
	v_pk_mul_f32 v[188:189], v[180:181], v[220:221]
	v_pk_mul_f32 v[190:191], v[182:183], v[220:221]
	v_exp_f32_e32 v184, v184
	v_exp_f32_e32 v185, v185
	v_exp_f32_e32 v186, v186
	v_exp_f32_e32 v187, v187
	v_exp_f32_e32 v188, v188
	v_exp_f32_e32 v189, v189
	v_exp_f32_e32 v190, v190
	v_exp_f32_e32 v191, v191
	v_pk_add_f32 v[184:185], v[184:185], v[222:223]
	v_pk_add_f32 v[186:187], v[186:187], v[222:223]
	v_pk_add_f32 v[188:189], v[188:189], v[222:223]
	v_pk_add_f32 v[190:191], v[190:191], v[222:223]
	v_rcp_f32_e32 v184, v184
	v_rcp_f32_e32 v185, v185
	v_rcp_f32_e32 v186, v186
	v_rcp_f32_e32 v187, v187
	v_rcp_f32_e32 v188, v188
	v_rcp_f32_e32 v189, v189
	v_rcp_f32_e32 v190, v190
	v_rcp_f32_e32 v191, v191
	v_pk_mul_f32 v[184:185], v[176:177], v[184:185]
	v_pk_mul_f32 v[186:187], v[178:179], v[186:187]
	v_pk_mul_f32 v[188:189], v[180:181], v[188:189]
	v_pk_mul_f32 v[190:191], v[182:183], v[190:191]
	v_cvt_pk_bf16_f32 v192, v184, v185
	v_cvt_pk_bf16_f32 v193, v186, v187
	v_cvt_pk_bf16_f32 v194, v188, v189
	v_cvt_pk_bf16_f32 v195, v190, v191
	global_store_dwordx4 v108, v[192:195], s[52:53]
	v_add_u32_e32 v108, 0x2000, v108
	s_add_i32 s56, s56, 1
	s_waitcnt vmcnt(11)
	s_cmp_lt_u32 s56, 0x4000
	s_cselect_b32 s57, 0x7ff, 7
	s_and_b32 s57, s56, s57
	s_cmp_eq_u32 s57, 0
	s_cbranch_scc0 .Lcv_b3_x
	s_cmp_lt_u32 s56, 0x4000
	s_cbranch_scc0 .Lcv_b3_s
	v_mov_b32_e32 v144, 0
	v_mov_b32_e32 v145, 0
	v_mov_b32_e32 v146, 0
	v_mov_b32_e32 v147, 0
	v_mov_b32_e32 v148, 0
	v_mov_b32_e32 v149, 0
	v_mov_b32_e32 v150, 0
	v_mov_b32_e32 v151, 0
	v_mov_b32_e32 v152, 0
	v_mov_b32_e32 v153, 0
	v_mov_b32_e32 v154, 0
	v_mov_b32_e32 v155, 0
	v_mov_b32_e32 v156, 0
	v_mov_b32_e32 v157, 0
	v_mov_b32_e32 v158, 0
	v_mov_b32_e32 v159, 0
	v_mov_b32_e32 v160, 0
	v_mov_b32_e32 v161, 0
	v_mov_b32_e32 v162, 0
	v_mov_b32_e32 v163, 0
	v_mov_b32_e32 v164, 0
	v_mov_b32_e32 v165, 0
	v_mov_b32_e32 v166, 0
	v_mov_b32_e32 v167, 0
	s_branch .Lcv_b3_x

; __device__ __forceinline__ float silu(float x) { return x * __builtin_amdgcn_rcpf(1.0f + __expf(-x)); }
; __device__ void phase_conv(const Params& p, unsigned char* smem, const int rep) {
;     ...
;         const bool samp = row >= NPROMPT;
;         const int t = samp ? ((row - NPROMPT) & 7) : (row & 2047);
;         const int b = samp ? ((row - NPROMPT) >> 3) : (row >> 11);
;         if (r == 0 || t == 0) {
; #pragma unroll
;           for (int k = 1; k <= 3; ++k) {
;             float hv[8];
;             if (t - k >= 0) {
;               unpack8(*(const u32x4*)(proj + (size_t)(row - k) * PROJ_LD + 2048 + ch0), hv);
;             } else if (samp) {
;               const float* sp = p.state_conv + ((size_t)b * 3 + (t - k + 3)) * 4096 + ch0;
;               const float4 s0 = *(const float4*)sp, s1 = *(const float4*)(sp + 4);
;               hv[0] = s0.x; hv[1] = s0.y; hv[2] = s0.z; hv[3] = s0.w; hv[4] = s1.x; hv[5] = s1.y; hv[6] = s1.z; hv[7] = s1.w;
;             } else {
; #pragma unroll
;               for (int q = 0; q < 8; ++q) hv[q] = 0.f;
;             }
; #pragma unroll
;             for (int q = 0; q < 8; ++q) {
;               if (k == 1) hm1[q] = hv[q];
;               if (k == 2) hm2[q] = hv[q];
;               if (k == 3) hm3[q] = hv[q];
;             }
;           }
;         }
;         float xc[8], o[8];
;         unpack8(cur[q4], xc);
; #pragma unroll
;         for (int q = 0; q < 8; ++q) {
;           const float a = bs[q] + hm3[q] * wgt[0][q] + hm2[q] * wgt[1][q] + hm1[q] * wgt[2][q] + xc[q] * wgt[3][q];
;           o[q] = silu(a);
;           hm3[q] = hm2[q]; hm2[q] = hm1[q]; hm1[q] = xc[q];
;         }
;         u32x4 ov;
;         ov.x = pack2(o[0], o[1]); ov.y = pack2(o[2], o[3]); ov.z = pack2(o[4], o[5]); ov.w = pack2(o[6], o[7]);
;         *(u32x4*)(xbcc + (size_t)row * 4096 + ch0) = ov;
;       }
; #pragma unroll
;       for (int q = 0; q < 4; ++q) cur[q] = nxt[q];
;     }
.Lcv_b3_x:
	v_lshlrev_b32_e32 v168, 16, v140
	v_and_b32_e32 v169, 0xffff0000, v140
	v_lshlrev_b32_e32 v170, 16, v141
	v_and_b32_e32 v171, 0xffff0000, v141
	v_lshlrev_b32_e32 v172, 16, v142
	v_and_b32_e32 v173, 0xffff0000, v142
	v_lshlrev_b32_e32 v174, 16, v143
	v_and_b32_e32 v175, 0xffff0000, v143
	v_pk_fma_f32 v[176:177], v[32:33], v[144:145], v[36:37]
	v_pk_fma_f32 v[178:179], v[34:35], v[146:147], v[38:39]
	v_pk_fma_f32 v[180:181], v[24:25], v[148:149], v[28:29]
	v_pk_fma_f32 v[182:183], v[26:27], v[150:151], v[30:31]
	v_pk_fma_f32 v[176:177], v[16:17], v[152:153], v[176:177]
	v_pk_fma_f32 v[178:179], v[18:19], v[154:155], v[178:179]
	v_pk_fma_f32 v[180:181], v[0:1], v[156:157], v[180:181]
	v_pk_fma_f32 v[182:183], v[2:3], v[158:159], v[182:183]
	v_pk_fma_f32 v[176:177], v[8:9], v[160:161], v[176:177]
	v_pk_fma_f32 v[178:179], v[10:11], v[162:163], v[178:179]
	v_pk_fma_f32 v[180:181], v[4:5], v[164:165], v[180:181]
	v_pk_fma_f32 v[182:183], v[6:7], v[166:167], v[182:183]
	v_pk_fma_f32 v[176:177], v[12:13], v[168:169], v[176:177]
	v_pk_fma_f32 v[178:179], v[14:15], v[170:171], v[178:179]
	v_pk_fma_f32 v[180:181], v[20:21], v[172:173], v[180:181]
	v_pk_fma_f32 v[182:183], v[22:23], v[174:175], v[182:183]
	v_pk_mul_f32 v[184:185], v[176:177], v[220:221]
	v_pk_mul_f32 v[186:187], v[178:179], v[220:221]
	v_pk_mul_f32 v[188:189], v[180:181], v[220:221]
	v_pk_mul_f32 v[190:191], v[182:183], v[220:221]
	v_exp_f32_e32 v184, v184
	v_exp_f32_e32 v185, v185
	v_exp_f32_e32 v186, v186
	v_exp_f32_e32 v187, v187
	v_exp_f32_e32 v188, v188
	v_exp_f32_e32 v189, v189
	v_exp_f32_e32 v190, v190
	v_exp_f32_e32 v191, v191
	v_pk_add_f32 v[184:185], v[184:185], v[222:223]
	v_pk_add_f32 v[186:187], v[186:187], v[222:223]
	v_pk_add_f32 v[188:189], v[188:189], v[222:223]
	v_pk_add_f32 v[190:191], v[190:191], v[222:223]
	v_rcp_f32_e32 v184, v184
	v_rcp_f32_e32 v185, v185
	v_rcp_f32_e32 v186, v186
	v_rcp_f32_e32 v187, v187
	v_rcp_f32_e32 v188, v188
	v_rcp_f32_e32 v189, v189
	v_rcp_f32_e32 v190, v190
	v_rcp_f32_e32 v191, v191
	v_pk_mul_f32 v[184:185], v[176:177], v[184:185]
	v_pk_mul_f32 v[186:187], v[178:179], v[186:187]
	v_pk_mul_f32 v[188:189], v[180:181], v[188:189]
	v_pk_mul_f32 v[190:191], v[182:183], v[190:191]
	v_cvt_pk_bf16_f32 v192, v184, v185
	v_cvt_pk_bf16_f32 v193, v186, v187
	v_cvt_pk_bf16_f32 v194, v188, v189
	v_cvt_pk_bf16_f32 v195, v190, v191
	global_store_dwordx4 v108, v[192:195], s[52:53]
	v_add_u32_e32 v108, 0x2000, v108
	s_add_i32 s56, s56, 1
	s_add_i32 s60, s60, 1
	s_cmp_lt_u32 s60, 8
	s_cbranch_scc1 .Lcv_loop
	s_waitcnt vmcnt(7)
	s_cmp_lt_u32 s56, 0x4000
	s_cselect_b32 s57, 0x7ff, 7
	s_and_b32 s57, s56, s57
	s_cmp_eq_u32 s57, 0
	s_cbranch_scc0 .Lcv_c0_x
	s_cmp_lt_u32 s56, 0x4000
	s_cbranch_scc0 .Lcv_c0_s
	v_mov_b32_e32 v152, 0
	v_mov_b32_e32 v153, 0
	v_mov_b32_e32 v154, 0
	v_mov_b32_e32 v155, 0
	v_mov_b32_e32 v156, 0
	v_mov_b32_e32 v157, 0
	v_mov_b32_e32 v158, 0
	v_mov_b32_e32 v159, 0
	v_mov_b32_e32 v160, 0
	v_mov_b32_e32 v161, 0
	v_mov_b32_e32 v162, 0
	v_mov_b32_e32 v163, 0
	v_mov_b32_e32 v164, 0
	v_mov_b32_e32 v165, 0
	v_mov_b32_e32 v166, 0
	v_mov_b32_e32 v167, 0
	v_mov_b32_e32 v168, 0
	v_mov_b32_e32 v169, 0
	v_mov_b32_e32 v170, 0
	v_mov_b32_e32 v171, 0
	v_mov_b32_e32 v172, 0
	v_mov_b32_e32 v173, 0
	v_mov_b32_e32 v174, 0
	v_mov_b32_e32 v175, 0
	s_branch .Lcv_c0_x

; __device__ __forceinline__ float silu(float x) { return x * __builtin_amdgcn_rcpf(1.0f + __expf(-x)); }
; __device__ void phase_conv(const Params& p, unsigned char* smem, const int rep) {
;     ...
;         const bool samp = row >= NPROMPT;
;         const int t = samp ? ((row - NPROMPT) & 7) : (row & 2047);
;         const int b = samp ? ((row - NPROMPT) >> 3) : (row >> 11);
;         if (r == 0 || t == 0) {
; #pragma unroll
;           for (int k = 1; k <= 3; ++k) {
;             float hv[8];
;             if (t - k >= 0) {
;               unpack8(*(const u32x4*)(proj + (size_t)(row - k) * PROJ_LD + 2048 + ch0), hv);
;             } else if (samp) {
;               const float* sp = p.state_conv + ((size_t)b * 3 + (t - k + 3)) * 4096 + ch0;
;               const float4 s0 = *(const float4*)sp, s1 = *(const float4*)(sp + 4);
;               hv[0] = s0.x; hv[1] = s0.y; hv[2] = s0.z; hv[3] = s0.w; hv[4] = s1.x; hv[5] = s1.y; hv[6] = s1.z; hv[7] = s1.w;
;             } else {
; #pragma unroll
;               for (int q = 0; q < 8; ++q) hv[q] = 0.f;
;     ...
;         float xc[8], o[8];
;         unpack8(cur[q4], xc);
; #pragma unroll
;         for (int q = 0; q < 8; ++q) {
;           const float a = bs[q] + hm3[q] * wgt[0][q] + hm2[q] * wgt[1][q] + hm1[q] * wgt[2][q] + xc[q] * wgt[3][q];
;           o[q] = silu(a);
;           hm3[q] = hm2[q]; hm2[q] = hm1[q]; hm1[q] = xc[q];
;         }
;         u32x4 ov;
;         ov.x = pack2(o[0], o[1]); ov.y = pack2(o[2], o[3]); ov.z = pack2(o[4], o[5]); ov.w = pack2(o[6], o[7]);
;         *(u32x4*)(xbcc + (size_t)row * 4096 + ch0) = ov;
.Lcv_c0_x:
	v_lshlrev_b32_e32 v144, 16, v112
	v_and_b32_e32 v145, 0xffff0000, v112
	v_lshlrev_b32_e32 v146, 16, v113
	v_and_b32_e32 v147, 0xffff0000, v113
	v_lshlrev_b32_e32 v148, 16, v114
	v_and_b32_e32 v149, 0xffff0000, v114
	v_lshlrev_b32_e32 v150, 16, v115
	v_and_b32_e32 v151, 0xffff0000, v115
	v_pk_fma_f32 v[176:177], v[32:33], v[152:153], v[36:37]
	v_pk_fma_f32 v[178:179], v[34:35], v[154:155], v[38:39]
	v_pk_fma_f32 v[180:181], v[24:25], v[156:157], v[28:29]
	v_pk_fma_f32 v[182:183], v[26:27], v[158:159], v[30:31]
	v_pk_fma_f32 v[176:177], v[16:17], v[160:161], v[176:177]
	v_pk_fma_f32 v[178:179], v[18:19], v[162:163], v[178:179]
	v_pk_fma_f32 v[180:181], v[0:1], v[164:165], v[180:181]
	v_pk_fma_f32 v[182:183], v[2:3], v[166:167], v[182:183]
	v_pk_fma_f32 v[176:177], v[8:9], v[168:169], v[176:177]
	v_pk_fma_f32 v[178:179], v[10:11], v[170:171], v[178:179]
	v_pk_fma_f32 v[180:181], v[4:5], v[172:173], v[180:181]
	v_pk_fma_f32 v[182:183], v[6:7], v[174:175], v[182:183]
	v_pk_fma_f32 v[176:177], v[12:13], v[144:145], v[176:177]
	v_pk_fma_f32 v[178:179], v[14:15], v[146:147], v[178:179]
	v_pk_fma_f32 v[180:181], v[20:21], v[148:149], v[180:181]
	v_pk_fma_f32 v[182:183], v[22:23], v[150:151], v[182:183]
	v_pk_mul_f32 v[184:185], v[176:177], v[220:221]
	v_pk_mul_f32 v[186:187], v[178:179], v[220:221]
	v_pk_mul_f32 v[188:189], v[180:181], v[220:221]
	v_pk_mul_f32 v[190:191], v[182:183], v[220:221]
	v_exp_f32_e32 v184, v184
	v_exp_f32_e32 v185, v185
	v_exp_f32_e32 v186, v186
	v_exp_f32_e32 v187, v187
	v_exp_f32_e32 v188, v188
	v_exp_f32_e32 v189, v189
	v_exp_f32_e32 v190, v190
	v_exp_f32_e32 v191, v191
	v_pk_add_f32 v[184:185], v[184:185], v[222:223]
	v_pk_add_f32 v[186:187], v[186:187], v[222:223]
	v_pk_add_f32 v[188:189], v[188:189], v[222:223]
	v_pk_add_f32 v[190:191], v[190:191], v[222:223]
	v_rcp_f32_e32 v184, v184
	v_rcp_f32_e32 v185, v185
	v_rcp_f32_e32 v186, v186
	v_rcp_f32_e32 v187, v187
	v_rcp_f32_e32 v188, v188
	v_rcp_f32_e32 v189, v189
	v_rcp_f32_e32 v190, v190
	v_rcp_f32_e32 v191, v191
	v_pk_mul_f32 v[184:185], v[176:177], v[184:185]
	v_pk_mul_f32 v[186:187], v[178:179], v[186:187]
	v_pk_mul_f32 v[188:189], v[180:181], v[188:189]
	v_pk_mul_f32 v[190:191], v[182:183], v[190:191]
	v_cvt_pk_bf16_f32 v192, v184, v185
	v_cvt_pk_bf16_f32 v193, v186, v187
	v_cvt_pk_bf16_f32 v194, v188, v189
	v_cvt_pk_bf16_f32 v195, v190, v191
	global_store_dwordx4 v108, v[192:195], s[52:53]
	v_add_u32_e32 v108, 0x2000, v108
	s_add_i32 s56, s56, 1
	s_waitcnt vmcnt(7)
	s_cmp_lt_u32 s56, 0x4000
	s_cselect_b32 s57, 0x7ff, 7
	s_and_b32 s57, s56, s57
	s_cmp_eq_u32 s57, 0
	s_cbranch_scc0 .Lcv_c1_x
	s_cmp_lt_u32 s56, 0x4000
	s_cbranch_scc0 .Lcv_c1_s
	v_mov_b32_e32 v160, 0
	v_mov_b32_e32 v161, 0
	v_mov_b32_e32 v162, 0
	v_mov_b32_e32 v163, 0
	v_mov_b32_e32 v164, 0
	v_mov_b32_e32 v165, 0
	v_mov_b32_e32 v166, 0
	v_mov_b32_e32 v167, 0
	v_mov_b32_e32 v168, 0
	v_mov_b32_e32 v169, 0
	v_mov_b32_e32 v170, 0
	v_mov_b32_e32 v171, 0
	v_mov_b32_e32 v172, 0
	v_mov_b32_e32 v173, 0
	v_mov_b32_e32 v174, 0
	v_mov_b32_e32 v175, 0
	v_mov_b32_e32 v144, 0
	v_mov_b32_e32 v145, 0
	v_mov_b32_e32 v146, 0
	v_mov_b32_e32 v147, 0
	v_mov_b32_e32 v148, 0
	v_mov_b32_e32 v149, 0
	v_mov_b32_e32 v150, 0
	v_mov_b32_e32 v151, 0
	s_branch .Lcv_c1_x

; __device__ __forceinline__ float silu(float x) { return x * __builtin_amdgcn_rcpf(1.0f + __expf(-x)); }
; __device__ void phase_conv(const Params& p, unsigned char* smem, const int rep) {
;     ...
;         const bool samp = row >= NPROMPT;
;         const int t = samp ? ((row - NPROMPT) & 7) : (row & 2047);
;         const int b = samp ? ((row - NPROMPT) >> 3) : (row >> 11);
;         if (r == 0 || t == 0) {
; #pragma unroll
;           for (int k = 1; k <= 3; ++k) {
;             float hv[8];
;             if (t - k >= 0) {
;               unpack8(*(const u32x4*)(proj + (size_t)(row - k) * PROJ_LD + 2048 + ch0), hv);
;             } else if (samp) {
;               const float* sp = p.state_conv + ((size_t)b * 3 + (t - k + 3)) * 4096 + ch0;
;               const float4 s0 = *(const float4*)sp, s1 = *(const float4*)(sp + 4);
;               hv[0] = s0.x; hv[1] = s0.y; hv[2] = s0.z; hv[3] = s0.w; hv[4] = s1.x; hv[5] = s1.y; hv[6] = s1.z; hv[7] = s1.w;
;             } else {
; #pragma unroll
;               for (int q = 0; q < 8; ++q) hv[q] = 0.f;
;     ...
;         float xc[8], o[8];
;         unpack8(cur[q4], xc);
; #pragma unroll
;         for (int q = 0; q < 8; ++q) {
;           const float a = bs[q] + hm3[q] * wgt[0][q] + hm2[q] * wgt[1][q] + hm1[q] * wgt[2][q] + xc[q] * wgt[3][q];
;           o[q] = silu(a);
;           hm3[q] = hm2[q]; hm2[q] = hm1[q]; hm1[q] = xc[q];
;         }
;         u32x4 ov;
;         ov.x = pack2(o[0], o[1]); ov.y = pack2(o[2], o[3]); ov.z = pack2(o[4], o[5]); ov.w = pack2(o[6], o[7]);
;         *(u32x4*)(xbcc + (size_t)row * 4096 + ch0) = ov;
.Lcv_c1_x:
	v_lshlrev_b32_e32 v152, 16, v116
	v_and_b32_e32 v153, 0xffff0000, v116
	v_lshlrev_b32_e32 v154, 16, v117
	v_and_b32_e32 v155, 0xffff0000, v117
	v_lshlrev_b32_e32 v156, 16, v118
	v_and_b32_e32 v157, 0xffff0000, v118
	v_lshlrev_b32_e32 v158, 16, v119
	v_and_b32_e32 v159, 0xffff0000, v119
	v_pk_fma_f32 v[176:177], v[32:33], v[160:161], v[36:37]
	v_pk_fma_f32 v[178:179], v[34:35], v[162:163], v[38:39]
	v_pk_fma_f32 v[180:181], v[24:25], v[164:165], v[28:29]
	v_pk_fma_f32 v[182:183], v[26:27], v[166:167], v[30:31]
	v_pk_fma_f32 v[176:177], v[16:17], v[168:169], v[176:177]
	v_pk_fma_f32 v[178:179], v[18:19], v[170:171], v[178:179]
	v_pk_fma_f32 v[180:181], v[0:1], v[172:173], v[180:181]
	v_pk_fma_f32 v[182:183], v[2:3], v[174:175], v[182:183]
	v_pk_fma_f32 v[176:177], v[8:9], v[144:145], v[176:177]
	v_pk_fma_f32 v[178:179], v[10:11], v[146:147], v[178:179]
	v_pk_fma_f32 v[180:181], v[4:5], v[148:149], v[180:181]
	v_pk_fma_f32 v[182:183], v[6:7], v[150:151], v[182:183]
	v_pk_fma_f32 v[176:177], v[12:13], v[152:153], v[176:177]
	v_pk_fma_f32 v[178:179], v[14:15], v[154:155], v[178:179]
	v_pk_fma_f32 v[180:181], v[20:21], v[156:157], v[180:181]
	v_pk_fma_f32 v[182:183], v[22:23], v[158:159], v[182:183]
	v_pk_mul_f32 v[184:185], v[176:177], v[220:221]
	v_pk_mul_f32 v[186:187], v[178:179], v[220:221]
	v_pk_mul_f32 v[188:189], v[180:181], v[220:221]
	v_pk_mul_f32 v[190:191], v[182:183], v[220:221]
	v_exp_f32_e32 v184, v184
	v_exp_f32_e32 v185, v185
	v_exp_f32_e32 v186, v186
	v_exp_f32_e32 v187, v187
	v_exp_f32_e32 v188, v188
	v_exp_f32_e32 v189, v189
	v_exp_f32_e32 v190, v190
	v_exp_f32_e32 v191, v191
	v_pk_add_f32 v[184:185], v[184:185], v[222:223]
	v_pk_add_f32 v[186:187], v[186:187], v[222:223]
	v_pk_add_f32 v[188:189], v[188:189], v[222:223]
	v_pk_add_f32 v[190:191], v[190:191], v[222:223]
	v_rcp_f32_e32 v184, v184
	v_rcp_f32_e32 v185, v185
	v_rcp_f32_e32 v186, v186
	v_rcp_f32_e32 v187, v187
	v_rcp_f32_e32 v188, v188
	v_rcp_f32_e32 v189, v189
	v_rcp_f32_e32 v190, v190
	v_rcp_f32_e32 v191, v191
	v_pk_mul_f32 v[184:185], v[176:177], v[184:185]
	v_pk_mul_f32 v[186:187], v[178:179], v[186:187]
	v_pk_mul_f32 v[188:189], v[180:181], v[188:189]
	v_pk_mul_f32 v[190:191], v[182:183], v[190:191]
	v_cvt_pk_bf16_f32 v192, v184, v185
	v_cvt_pk_bf16_f32 v193, v186, v187
	v_cvt_pk_bf16_f32 v194, v188, v189
	v_cvt_pk_bf16_f32 v195, v190, v191
	global_store_dwordx4 v108, v[192:195], s[52:53]
	v_add_u32_e32 v108, 0x2000, v108
	s_add_i32 s56, s56, 1
	s_waitcnt vmcnt(7)
	s_cmp_lt_u32 s56, 0x4000
	s_cselect_b32 s57, 0x7ff, 7
	s_and_b32 s57, s56, s57
	s_cmp_eq_u32 s57, 0
	s_cbranch_scc0 .Lcv_c2_x
	s_cmp_lt_u32 s56, 0x4000
	s_cbranch_scc0 .Lcv_c2_s
	v_mov_b32_e32 v168, 0
	v_mov_b32_e32 v169, 0
	v_mov_b32_e32 v170, 0
	v_mov_b32_e32 v171, 0
	v_mov_b32_e32 v172, 0
	v_mov_b32_e32 v173, 0
	v_mov_b32_e32 v174, 0
	v_mov_b32_e32 v175, 0
	v_mov_b32_e32 v144, 0
	v_mov_b32_e32 v145, 0
	v_mov_b32_e32 v146, 0
	v_mov_b32_e32 v147, 0
	v_mov_b32_e32 v148, 0
	v_mov_b32_e32 v149, 0
	v_mov_b32_e32 v150, 0
	v_mov_b32_e32 v151, 0
	v_mov_b32_e32 v152, 0
	v_mov_b32_e32 v153, 0
	v_mov_b32_e32 v154, 0
	v_mov_b32_e32 v155, 0
	v_mov_b32_e32 v156, 0
	v_mov_b32_e32 v157, 0
	v_mov_b32_e32 v158, 0
	v_mov_b32_e32 v159, 0
	s_branch .Lcv_c2_x

; __device__ __forceinline__ float silu(float x) { return x * __builtin_amdgcn_rcpf(1.0f + __expf(-x)); }
; __device__ void phase_conv(const Params& p, unsigned char* smem, const int rep) {
;     ...
;         const bool samp = row >= NPROMPT;
;         const int t = samp ? ((row - NPROMPT) & 7) : (row & 2047);
;         const int b = samp ? ((row - NPROMPT) >> 3) : (row >> 11);
;         if (r == 0 || t == 0) {
; #pragma unroll
;           for (int k = 1; k <= 3; ++k) {
;             float hv[8];
;             if (t - k >= 0) {
;               unpack8(*(const u32x4*)(proj + (size_t)(row - k) * PROJ_LD + 2048 + ch0), hv);
;             } else if (samp) {
;               const float* sp = p.state_conv + ((size_t)b * 3 + (t - k + 3)) * 4096 + ch0;
;               const float4 s0 = *(const float4*)sp, s1 = *(const float4*)(sp + 4);
;               hv[0] = s0.x; hv[1] = s0.y; hv[2] = s0.z; hv[3] = s0.w; hv[4] = s1.x; hv[5] = s1.y; hv[6] = s1.z; hv[7] = s1.w;
;             } else {
; #pragma unroll
;               for (int q = 0; q < 8; ++q) hv[q] = 0.f;
;     ...
;         float xc[8], o[8];
;         unpack8(cur[q4], xc);
; #pragma unroll
;         for (int q = 0; q < 8; ++q) {
;           const float a = bs[q] + hm3[q] * wgt[0][q] + hm2[q] * wgt[1][q] + hm1[q] * wgt[2][q] + xc[q] * wgt[3][q];
;           o[q] = silu(a);
;           hm3[q] = hm2[q]; hm2[q] = hm1[q]; hm1[q] = xc[q];
;         }
;         u32x4 ov;
;         ov.x = pack2(o[0], o[1]); ov.y = pack2(o[2], o[3]); ov.z = pack2(o[4], o[5]); ov.w = pack2(o[6], o[7]);
;         *(u32x4*)(xbcc + (size_t)row * 4096 + ch0) = ov;
.Lcv_c2_x:
	v_lshlrev_b32_e32 v160, 16, v120
	v_and_b32_e32 v161, 0xffff0000, v120
	v_lshlrev_b32_e32 v162, 16, v121
	v_and_b32_e32 v163, 0xffff0000, v121
	v_lshlrev_b32_e32 v164, 16, v122
	v_and_b32_e32 v165, 0xffff0000, v122
	v_lshlrev_b32_e32 v166, 16, v123
	v_and_b32_e32 v167, 0xffff0000, v123
	v_pk_fma_f32 v[176:177], v[32:33], v[168:169], v[36:37]
	v_pk_fma_f32 v[178:179], v[34:35], v[170:171], v[38:39]
	v_pk_fma_f32 v[180:181], v[24:25], v[172:173], v[28:29]
	v_pk_fma_f32 v[182:183], v[26:27], v[174:175], v[30:31]
	v_pk_fma_f32 v[176:177], v[16:17], v[144:145], v[176:177]
	v_pk_fma_f32 v[178:179], v[18:19], v[146:147], v[178:179]
	v_pk_fma_f32 v[180:181], v[0:1], v[148:149], v[180:181]
	v_pk_fma_f32 v[182:183], v[2:3], v[150:151], v[182:183]
	v_pk_fma_f32 v[176:177], v[8:9], v[152:153], v[176:177]
	v_pk_fma_f32 v[178:179], v[10:11], v[154:155], v[178:179]
	v_pk_fma_f32 v[180:181], v[4:5], v[156:157], v[180:181]
	v_pk_fma_f32 v[182:183], v[6:7], v[158:159], v[182:183]
	v_pk_fma_f32 v[176:177], v[12:13], v[160:161], v[176:177]
	v_pk_fma_f32 v[178:179], v[14:15], v[162:163], v[178:179]
	v_pk_fma_f32 v[180:181], v[20:21], v[164:165], v[180:181]
	v_pk_fma_f32 v[182:183], v[22:23], v[166:167], v[182:183]
	v_pk_mul_f32 v[184:185], v[176:177], v[220:221]
	v_pk_mul_f32 v[186:187], v[178:179], v[220:221]
	v_pk_mul_f32 v[188:189], v[180:181], v[220:221]
	v_pk_mul_f32 v[190:191], v[182:183], v[220:221]
	v_exp_f32_e32 v184, v184
	v_exp_f32_e32 v185, v185
	v_exp_f32_e32 v186, v186
	v_exp_f32_e32 v187, v187
	v_exp_f32_e32 v188, v188
	v_exp_f32_e32 v189, v189
	v_exp_f32_e32 v190, v190
	v_exp_f32_e32 v191, v191
	v_pk_add_f32 v[184:185], v[184:185], v[222:223]
	v_pk_add_f32 v[186:187], v[186:187], v[222:223]
	v_pk_add_f32 v[188:189], v[188:189], v[222:223]
	v_pk_add_f32 v[190:191], v[190:191], v[222:223]
	v_rcp_f32_e32 v184, v184
	v_rcp_f32_e32 v185, v185
	v_rcp_f32_e32 v186, v186
	v_rcp_f32_e32 v187, v187
	v_rcp_f32_e32 v188, v188
	v_rcp_f32_e32 v189, v189
	v_rcp_f32_e32 v190, v190
	v_rcp_f32_e32 v191, v191
	v_pk_mul_f32 v[184:185], v[176:177], v[184:185]
	v_pk_mul_f32 v[186:187], v[178:179], v[186:187]
	v_pk_mul_f32 v[188:189], v[180:181], v[188:189]
	v_pk_mul_f32 v[190:191], v[182:183], v[190:191]
	v_cvt_pk_bf16_f32 v192, v184, v185
	v_cvt_pk_bf16_f32 v193, v186, v187
	v_cvt_pk_bf16_f32 v194, v188, v189
	v_cvt_pk_bf16_f32 v195, v190, v191
	global_store_dwordx4 v108, v[192:195], s[52:53]
	v_add_u32_e32 v108, 0x2000, v108
	s_add_i32 s56, s56, 1
	s_waitcnt vmcnt(7)
	s_cmp_lt_u32 s56, 0x4000
	s_cselect_b32 s57, 0x7ff, 7
	s_and_b32 s57, s56, s57
	s_cmp_eq_u32 s57, 0
	s_cbranch_scc0 .Lcv_c3_x
	s_cmp_lt_u32 s56, 0x4000
	s_cbranch_scc0 .Lcv_c3_s
	v_mov_b32_e32 v144, 0
	v_mov_b32_e32 v145, 0
	v_mov_b32_e32 v146, 0
	v_mov_b32_e32 v147, 0
	v_mov_b32_e32 v148, 0
	v_mov_b32_e32 v149, 0
	v_mov_b32_e32 v150, 0
	v_mov_b32_e32 v151, 0
	v_mov_b32_e32 v152, 0
	v_mov_b32_e32 v153, 0
	v_mov_b32_e32 v154, 0
	v_mov_b32_e32 v155, 0
	v_mov_b32_e32 v156, 0
	v_mov_b32_e32 v157, 0
	v_mov_b32_e32 v158, 0
	v_mov_b32_e32 v159, 0
	v_mov_b32_e32 v160, 0
	v_mov_b32_e32 v161, 0
	v_mov_b32_e32 v162, 0
	v_mov_b32_e32 v163, 0
	v_mov_b32_e32 v164, 0
	v_mov_b32_e32 v165, 0
	v_mov_b32_e32 v166, 0
	v_mov_b32_e32 v167, 0
	s_branch .Lcv_c3_x

; __device__ __forceinline__ float silu(float x) { return x * __builtin_amdgcn_rcpf(1.0f + __expf(-x)); }
; __device__ void phase_conv(const Params& p, unsigned char* smem, const int rep) {
;     ...
;         float xc[8], o[8];
;         unpack8(cur[q4], xc);
; #pragma unroll
;         for (int q = 0; q < 8; ++q) {
;           const float a = bs[q] + hm3[q] * wgt[0][q] + hm2[q] * wgt[1][q] + hm1[q] * wgt[2][q] + xc[q] * wgt[3][q];
;           o[q] = silu(a);
;           hm3[q] = hm2[q]; hm2[q] = hm1[q]; hm1[q] = xc[q];
;         }
;         u32x4 ov;
;         ov.x = pack2(o[0], o[1]); ov.y = pack2(o[2], o[3]); ov.z = pack2(o[4], o[5]); ov.w = pack2(o[6], o[7]);
;         *(u32x4*)(xbcc + (size_t)row * 4096 + ch0) = ov;
.Lcv_c3_x:
	v_lshlrev_b32_e32 v168, 16, v124
	v_and_b32_e32 v169, 0xffff0000, v124
	v_lshlrev_b32_e32 v170, 16, v125
	v_and_b32_e32 v171, 0xffff0000, v125
	v_lshlrev_b32_e32 v172, 16, v126
	v_and_b32_e32 v173, 0xffff0000, v126
	v_lshlrev_b32_e32 v174, 16, v127
	v_and_b32_e32 v175, 0xffff0000, v127
	v_pk_fma_f32 v[176:177], v[32:33], v[144:145], v[36:37]
	v_pk_fma_f32 v[178:179], v[34:35], v[146:147], v[38:39]
	v_pk_fma_f32 v[180:181], v[24:25], v[148:149], v[28:29]
	v_pk_fma_f32 v[182:183], v[26:27], v[150:151], v[30:31]
	v_pk_fma_f32 v[176:177], v[16:17], v[152:153], v[176:177]
	v_pk_fma_f32 v[178:179], v[18:19], v[154:155], v[178:179]
	v_pk_fma_f32 v[180:181], v[0:1], v[156:157], v[180:181]
	v_pk_fma_f32 v[182:183], v[2:3], v[158:159], v[182:183]
	v_pk_fma_f32 v[176:177], v[8:9], v[160:161], v[176:177]
	v_pk_fma_f32 v[178:179], v[10:11], v[162:163], v[178:179]
	v_pk_fma_f32 v[180:181], v[4:5], v[164:165], v[180:181]
	v_pk_fma_f32 v[182:183], v[6:7], v[166:167], v[182:183]
	v_pk_fma_f32 v[176:177], v[12:13], v[168:169], v[176:177]
	v_pk_fma_f32 v[178:179], v[14:15], v[170:171], v[178:179]
	v_pk_fma_f32 v[180:181], v[20:21], v[172:173], v[180:181]
	v_pk_fma_f32 v[182:183], v[22:23], v[174:175], v[182:183]
	v_pk_mul_f32 v[184:185], v[176:177], v[220:221]
	v_pk_mul_f32 v[186:187], v[178:179], v[220:221]
	v_pk_mul_f32 v[188:189], v[180:181], v[220:221]
	v_pk_mul_f32 v[190:191], v[182:183], v[220:221]
	v_exp_f32_e32 v184, v184
	v_exp_f32_e32 v185, v185
	v_exp_f32_e32 v186, v186
	v_exp_f32_e32 v187, v187
	v_exp_f32_e32 v188, v188
	v_exp_f32_e32 v189, v189
	v_exp_f32_e32 v190, v190
	v_exp_f32_e32 v191, v191
	v_pk_add_f32 v[184:185], v[184:185], v[222:223]
	v_pk_add_f32 v[186:187], v[186:187], v[222:223]
	v_pk_add_f32 v[188:189], v[188:189], v[222:223]
	v_pk_add_f32 v[190:191], v[190:191], v[222:223]
	v_rcp_f32_e32 v184, v184
	v_rcp_f32_e32 v185, v185
	v_rcp_f32_e32 v186, v186
	v_rcp_f32_e32 v187, v187
	v_rcp_f32_e32 v188, v188
	v_rcp_f32_e32 v189, v189
	v_rcp_f32_e32 v190, v190
	v_rcp_f32_e32 v191, v191
	v_pk_mul_f32 v[184:185], v[176:177], v[184:185]
	v_pk_mul_f32 v[186:187], v[178:179], v[186:187]
	v_pk_mul_f32 v[188:189], v[180:181], v[188:189]
	v_pk_mul_f32 v[190:191], v[182:183], v[190:191]
	v_cvt_pk_bf16_f32 v192, v184, v185
	v_cvt_pk_bf16_f32 v193, v186, v187
	v_cvt_pk_bf16_f32 v194, v188, v189
	v_cvt_pk_bf16_f32 v195, v190, v191
	global_store_dwordx4 v108, v[192:195], s[52:53]
	v_add_u32_e32 v108, 0x2000, v108
	s_add_i32 s56, s56, 1
	s_branch .LBB0_1544
